# P3/P4 state loads and P6/P12 GEMM-output row loads marked sc1 (instead of nt / plain)
# baseline (speedup 1.0000x reference)
.LBB0_539:
	v_add_u32_e32 v0, s3, v213
	v_add_u32_e32 v12, 0x200, v0
	v_cmp_le_i32_e32 vcc, s62, v12
	s_and_saveexec_b64 s[56:57], vcc
	s_xor_b64 s[56:57], exec, s[56:57]
	s_cbranch_execz .LBB0_546
	v_cmp_gt_i32_e32 vcc, s62, v0
	s_and_saveexec_b64 s[58:59], vcc
	s_cbranch_execz .LBB0_545
	v_mul_hi_i32 v1, v0, s64
	v_lshrrev_b32_e32 v2, 31, v1
	v_ashrrev_i32_e32 v1, 11, v1
	v_add_u32_e32 v1, v1, v2
	v_mul_i32_i24_e32 v2, 0x2400, v1
	v_sub_u32_e32 v0, v0, v2
	v_bfe_i32 v3, v0, 6, 16
	v_mul_i32_i24_e32 v3, 0x2aab, v3
	v_lshrrev_b32_e32 v4, 31, v3
	v_lshrrev_b32_e32 v3, 17, v3
	v_add_u16_e32 v3, v3, v4
	v_lshrrev_b32_e32 v2, 6, v0
	v_mul_lo_u16_e32 v3, 12, v3
	v_and_b32_e32 v108, 3, v1
	v_sub_u16_e32 v2, v2, v3
	v_lshrrev_b32_e32 v3, 2, v0
	v_lshlrev_b32_e32 v1, 4, v1
	v_bfe_i32 v2, v2, 0, 16
	v_and_b32_e32 v3, 8, v3
	v_and_b32_e32 v110, 0xffffffc0, v1
	v_lshl_or_b32 v2, v2, 4, v3
	v_or_b32_e32 v24, 2, v110
	v_ashrrev_i32_e32 v1, 31, v0
	v_ashrrev_i32_e32 v3, 31, v2
	v_ashrrev_i32_e32 v25, 31, v24
	v_lshlrev_b64 v[36:37], 4, v[0:1]
	v_lshlrev_b64 v[38:39], 2, v[2:3]
	v_lshlrev_b64 v[24:25], 2, v[24:25]
	v_lshl_add_u64 v[112:113], s[8:9], 0, v[36:37]
	v_lshl_add_u64 v[114:115], s[10:11], 0, v[38:39]
	v_or_b32_e32 v24, v24, v108
	v_or_b32_e32 v10, 1, v110
	v_mad_u64_u32 v[26:27], s[60:61], v24, s63, v[112:113]
	v_mad_u64_u32 v[28:29], s[60:61], v24, s65, v[114:115]
	v_or_b32_e32 v24, 3, v110
	v_ashrrev_i32_e32 v111, 31, v110
	v_ashrrev_i32_e32 v11, 31, v10
	v_mad_i32_i24 v27, v25, s63, v27
	v_mad_i32_i24 v29, v25, s65, v29
	v_ashrrev_i32_e32 v25, 31, v24
	v_lshlrev_b64 v[0:1], 2, v[110:111]
	v_lshlrev_b64 v[16:17], 2, v[10:11]
	v_lshlrev_b64 v[24:25], 2, v[24:25]
	v_or_b32_e32 v0, v0, v108
	v_or_b32_e32 v16, v16, v108
	v_or_b32_e32 v24, v24, v108
	v_mad_u64_u32 v[2:3], s[60:61], v0, s63, v[112:113]
	v_mad_u64_u32 v[8:9], s[60:61], v0, s65, v[114:115]
	v_mad_u64_u32 v[12:13], s[60:61], v16, s63, v[112:113]
	v_mad_u64_u32 v[20:21], s[60:61], v16, s65, v[114:115]
	v_mad_u64_u32 v[30:31], s[60:61], v24, s63, v[112:113]
	v_mad_i32_i24 v3, v1, s63, v3
	v_mad_i32_i24 v9, v1, s65, v9
	v_mad_i32_i24 v13, v17, s63, v13
	v_mad_i32_i24 v21, v17, s65, v21
	v_mad_i32_i24 v31, v25, s63, v31
	global_load_dwordx4 v[0:3], v[2:3], off sc1
	s_nop 0
	global_load_dwordx4 v[4:7], v[8:9], off offset:16
	s_nop 0
	global_load_dwordx4 v[8:11], v[8:9], off
	s_nop 0
	global_load_dwordx4 v[12:15], v[12:13], off sc1
	s_nop 0
	global_load_dwordx4 v[16:19], v[20:21], off offset:16
	s_nop 0
	global_load_dwordx4 v[20:23], v[20:21], off
	s_nop 0
	global_load_dwordx4 v[32:35], v[28:29], off
	global_load_dwordx4 v[60:63], v[30:31], off sc1
	v_mad_u64_u32 v[30:31], s[60:61], v24, s65, v[114:115]
	v_mad_i32_i24 v31, v25, s65, v31
	global_load_dwordx4 v[52:55], v[30:31], off offset:16
	global_load_dwordx4 v[64:67], v[30:31], off
	s_nop 0
	global_load_dwordx4 v[24:27], v[26:27], off sc1
	s_nop 0
	global_load_dwordx4 v[28:31], v[28:29], off offset:16
	v_mad_i64_i32 v[40:41], s[60:61], v110, s66, 0
	v_mul_hi_u32_u24_e32 v42, 0x24000, v108
	v_mul_u32_u24_e32 v43, 0x24000, v108
	v_or_b32_e32 v41, v41, v42
	v_or_b32_e32 v40, v40, v43
	v_lshl_add_u64 v[116:117], v[40:41], 0, v[36:37]
	v_mad_i64_i32 v[36:37], s[60:61], v110, s67, 0
	v_mul_hi_u32_u24_e32 v40, 0x300, v108
	v_mul_u32_u24_e32 v41, 0x300, v108
	v_or_b32_e32 v37, v37, v40
	v_or_b32_e32 v36, v36, v41
	v_lshl_add_u64 v[118:119], v[36:37], 0, v[38:39]
	v_mov_b32_e32 v128, 0
	s_mov_b32 s79, 0
	v_mov_b32_e32 v129, v128
	v_mov_b32_e32 v122, v128
	v_mov_b32_e32 v123, v128
	v_mov_b32_e32 v124, v128
	v_mov_b32_e32 v125, v128
	v_mov_b32_e32 v126, v128
	v_mov_b32_e32 v127, v128
	s_waitcnt vmcnt(0)
	v_mov_b64_e32 v[36:37], v[60:61]
	v_mov_b64_e32 v[40:41], v[52:53]
	v_mov_b64_e32 v[44:45], v[64:65]
	v_mov_b64_e32 v[42:43], v[54:55]
	v_mov_b64_e32 v[46:47], v[66:67]
	v_mov_b64_e32 v[38:39], v[62:63]
	s_branch .LBB0_543

.LBB0_543:
	v_lshl_add_u64 v[120:121], s[42:43], 0, v[116:117]
	v_add_co_u32_e32 v48, vcc, s68, v120
	v_lshl_add_u64 v[68:69], s[42:43], 0, v[118:119]
	s_nop 0
	v_addc_co_u32_e32 v49, vcc, 0, v121, vcc
	v_add_co_u32_e32 v56, vcc, s69, v68
	v_lshl_add_u64 v[50:51], v[68:69], 0, s[14:15]
	s_nop 0
	v_addc_co_u32_e32 v57, vcc, 0, v69, vcc
	v_add_co_u32_e32 v58, vcc, s70, v120
	v_lshl_add_u64 v[70:71], v[68:69], 0, s[18:19]
	s_nop 0
	v_addc_co_u32_e32 v59, vcc, 0, v121, vcc
	global_load_dwordx4 v[72:75], v[48:49], off sc1
	s_nop 0
	global_load_dwordx4 v[48:51], v[50:51], off offset:16
	s_nop 0
	global_load_dwordx4 v[96:99], v[56:57], off
	global_load_dwordx4 v[92:95], v[56:57], off offset:3072
	global_load_dwordx4 v[80:83], v[58:59], off sc1
	s_nop 0
	global_load_dwordx4 v[56:59], v[70:71], off offset:16
	v_add_co_u32_e32 v70, vcc, s71, v120
	v_lshl_add_u64 v[76:77], v[68:69], 0, s[22:23]
	s_nop 0
	v_addc_co_u32_e32 v71, vcc, 0, v121, vcc
	v_add_co_u32_e32 v88, vcc, s72, v68
	global_load_dwordx4 v[84:87], v[70:71], off sc1
	s_nop 0
	global_load_dwordx4 v[76:79], v[76:77], off offset:16
	v_addc_co_u32_e32 v89, vcc, 0, v69, vcc
	v_add_co_u32_e32 v70, vcc, s73, v120
	v_lshlrev_b32_e32 v134, 16, v0
	s_nop 0
	v_addc_co_u32_e32 v71, vcc, 0, v121, vcc
	global_load_dwordx4 v[100:103], v[88:89], off offset:2048
	s_nop 0
	global_load_dwordx4 v[88:91], v[70:71], off sc1
	v_lshl_add_u64 v[70:71], v[68:69], 0, s[26:27]
	v_add_co_u32_e32 v68, vcc, s74, v68
	v_and_b32_e32 v135, 0xffff0000, v0
	s_nop 0
	v_addc_co_u32_e32 v69, vcc, 0, v69, vcc
	global_load_dwordx4 v[104:107], v[68:69], off offset:1024
	s_nop 0
	global_load_dwordx4 v[68:71], v[70:71], off offset:16
	v_cvt_pk_bf16_f32 v130, v122, v123
	v_lshlrev_b32_e32 v136, 16, v12
	v_and_b32_e32 v137, 0xffff0000, v12
	v_pk_fma_f32 v[122:123], v[122:123], v[8:9], v[134:135]
	v_cvt_pk_bf16_f32 v131, v124, v125
	v_cvt_pk_bf16_f32 v134, v122, v123
	v_pk_fma_f32 v[122:123], v[20:21], v[122:123], v[136:137]
	v_lshlrev_b32_e32 v136, 16, v1
	v_and_b32_e32 v137, 0xffff0000, v1
	v_lshlrev_b32_e32 v140, 16, v13
	v_and_b32_e32 v141, 0xffff0000, v13
	v_pk_fma_f32 v[124:125], v[124:125], v[10:11], v[136:137]
	v_lshlrev_b32_e32 v136, 16, v2
	v_and_b32_e32 v137, 0xffff0000, v2
	v_cvt_pk_bf16_f32 v132, v126, v127
	v_cvt_pk_bf16_f32 v135, v124, v125
	v_pk_fma_f32 v[124:125], v[22:23], v[124:125], v[140:141]
	v_lshlrev_b32_e32 v140, 16, v14
	v_and_b32_e32 v141, 0xffff0000, v14
	v_pk_fma_f32 v[126:127], v[126:127], v[4:5], v[136:137]
	v_lshlrev_b32_e32 v146, 16, v26
	v_and_b32_e32 v147, 0xffff0000, v26
	v_cvt_pk_bf16_f32 v136, v126, v127
	v_pk_fma_f32 v[150:151], v[16:17], v[126:127], v[140:141]
	v_lshlrev_b32_e32 v126, 16, v3
	v_and_b32_e32 v127, 0xffff0000, v3
	v_cvt_pk_bf16_f32 v133, v128, v129
	v_pk_fma_f32 v[126:127], v[128:129], v[6:7], v[126:127]
	v_pk_fma_f32 v[128:129], v[28:29], v[150:151], v[146:147]
	v_add_co_u32_e32 v146, vcc, s75, v120
	v_lshlrev_b32_e32 v152, 16, v15
	s_nop 0
	v_addc_co_u32_e32 v147, vcc, 0, v121, vcc
	global_store_dwordx4 v[146:147], v[130:133], off sc1
	v_and_b32_e32 v153, 0xffff0000, v15
	v_cvt_pk_bf16_f32 v137, v126, v127
	v_add_co_u32_e32 v130, vcc, s76, v120
	v_pk_fma_f32 v[152:153], v[18:19], v[126:127], v[152:153]
	s_nop 0
	v_addc_co_u32_e32 v131, vcc, 0, v121, vcc
	global_store_dwordx4 v[130:131], v[134:137], off sc1
	v_add_co_u32_e32 v130, vcc, 0x14924000, v120
	v_cvt_pk_bf16_f32 v138, v122, v123
	v_cvt_pk_bf16_f32 v139, v124, v125
	v_cvt_pk_bf16_f32 v140, v150, v151
	v_cvt_pk_bf16_f32 v141, v152, v153
	v_addc_co_u32_e32 v131, vcc, 0, v121, vcc
	v_lshlrev_b32_e32 v142, 16, v24
	v_and_b32_e32 v143, 0xffff0000, v24
	v_lshlrev_b32_e32 v144, 16, v25
	v_and_b32_e32 v145, 0xffff0000, v25
	v_lshlrev_b32_e32 v148, 16, v27
	v_and_b32_e32 v149, 0xffff0000, v27
	global_store_dwordx4 v[130:131], v[138:141], off sc1
	v_add_co_u32_e32 v130, vcc, 0x149b4000, v120
	s_cmp_gt_u32 s79, 55
	v_pk_fma_f32 v[126:127], v[32:33], v[122:123], v[142:143]
	v_pk_fma_f32 v[122:123], v[34:35], v[124:125], v[144:145]
	v_pk_fma_f32 v[124:125], v[30:31], v[152:153], v[148:149]
	v_addc_co_u32_e32 v131, vcc, 0, v121, vcc
	s_cselect_b64 s[60:61], -1, 0
	v_cvt_pk_bf16_f32 v142, v126, v127
	v_cvt_pk_bf16_f32 v143, v122, v123
	v_cvt_pk_bf16_f32 v144, v128, v129
	v_cvt_pk_bf16_f32 v145, v124, v125
	s_and_b64 vcc, exec, s[60:61]
	global_store_dwordx4 v[130:131], v[142:145], off sc1
	s_cbranch_vccnz .LBB0_542
	v_add_u32_e32 v34, s79, v110
	v_add_u32_e32 v0, 8, v34
	v_add_u32_e32 v10, 9, v34
	v_add_u32_e32 v24, 10, v34
	v_add_u32_e32 v34, 11, v34
	v_ashrrev_i32_e32 v1, 31, v0
	v_ashrrev_i32_e32 v11, 31, v10
	v_ashrrev_i32_e32 v25, 31, v24
	v_ashrrev_i32_e32 v35, 31, v34
	v_lshlrev_b64 v[0:1], 2, v[0:1]
	v_lshlrev_b64 v[16:17], 2, v[10:11]
	v_lshlrev_b64 v[24:25], 2, v[24:25]
	v_lshlrev_b64 v[40:41], 2, v[34:35]
	v_or_b32_e32 v0, v0, v108
	v_or_b32_e32 v16, v16, v108
	v_or_b32_e32 v24, v24, v108
	v_or_b32_e32 v40, v40, v108
	v_mad_u64_u32 v[2:3], s[80:81], v0, s63, v[112:113]
	v_mad_u64_u32 v[8:9], s[80:81], v0, s65, v[114:115]
	v_mad_u64_u32 v[12:13], s[80:81], v16, s63, v[112:113]
	v_mad_u64_u32 v[20:21], s[80:81], v16, s65, v[114:115]
	v_mad_u64_u32 v[26:27], s[80:81], v24, s63, v[112:113]
	v_mad_u64_u32 v[32:33], s[80:81], v24, s65, v[114:115]
	v_mad_u64_u32 v[36:37], s[80:81], v40, s63, v[112:113]
	v_mad_u64_u32 v[44:45], s[80:81], v40, s65, v[114:115]
	v_mad_i32_i24 v3, v1, s63, v3
	v_mad_i32_i24 v9, v1, s65, v9
	v_mad_i32_i24 v13, v17, s63, v13
	v_mad_i32_i24 v21, v17, s65, v21
	v_mad_i32_i24 v27, v25, s63, v27
	v_mad_i32_i24 v33, v25, s65, v33
	v_mad_i32_i24 v37, v41, s63, v37
	v_mad_i32_i24 v45, v41, s65, v45
	global_load_dwordx4 v[0:3], v[2:3], off sc1
	s_nop 0
	global_load_dwordx4 v[4:7], v[8:9], off offset:16
	s_nop 0
	global_load_dwordx4 v[8:11], v[8:9], off
	s_nop 0
	global_load_dwordx4 v[12:15], v[12:13], off sc1
	s_nop 0
	global_load_dwordx4 v[16:19], v[20:21], off offset:16
	s_nop 0
	global_load_dwordx4 v[20:23], v[20:21], off
	s_nop 0
	global_load_dwordx4 v[24:27], v[26:27], off sc1
	s_nop 0
	global_load_dwordx4 v[28:31], v[32:33], off offset:16
	s_nop 0
	global_load_dwordx4 v[32:35], v[32:33], off
	s_nop 0
	global_load_dwordx4 v[36:39], v[36:37], off sc1
	s_nop 0
	global_load_dwordx4 v[40:43], v[44:45], off offset:16
	s_nop 0
	global_load_dwordx4 v[44:47], v[44:45], off
	s_branch .LBB0_542

.LBB0_546:
	s_andn2_saveexec_b64 s[56:57], s[56:57]
	s_cbranch_execz .LBB0_538
	v_mul_hi_i32 v1, v0, s64
	v_lshrrev_b32_e32 v2, 31, v1
	v_ashrrev_i32_e32 v1, 11, v1
	v_add_u32_e32 v1, v1, v2
	v_mul_i32_i24_e32 v2, 0x2400, v1
	v_sub_u32_e32 v0, v0, v2
	v_bfe_i32 v3, v0, 6, 16
	v_mul_i32_i24_e32 v3, 0x2aab, v3
	v_lshrrev_b32_e32 v4, 31, v3
	v_lshrrev_b32_e32 v3, 17, v3
	v_add_u16_e32 v3, v3, v4
	v_lshrrev_b32_e32 v2, 6, v0
	v_mul_lo_u16_e32 v3, 12, v3
	v_and_b32_e32 v120, 3, v1
	v_sub_u16_e32 v2, v2, v3
	v_lshrrev_b32_e32 v3, 2, v0
	v_lshlrev_b32_e32 v1, 4, v1
	v_bfe_i32 v2, v2, 0, 16
	v_and_b32_e32 v3, 8, v3
	v_and_b32_e32 v122, 0xffffffc0, v1
	v_lshl_or_b32 v2, v2, 4, v3
	v_or_b32_e32 v10, 1, v122
	v_ashrrev_i32_e32 v1, 31, v0
	v_ashrrev_i32_e32 v3, 31, v2
	v_ashrrev_i32_e32 v123, 31, v122
	v_ashrrev_i32_e32 v11, 31, v10
	v_lshlrev_b64 v[36:37], 4, v[0:1]
	v_lshlrev_b64 v[38:39], 2, v[2:3]
	v_lshlrev_b64 v[0:1], 2, v[122:123]
	v_lshlrev_b64 v[14:15], 2, v[10:11]
	v_lshl_add_u64 v[124:125], s[8:9], 0, v[36:37]
	v_lshl_add_u64 v[126:127], s[10:11], 0, v[38:39]
	v_or_b32_e32 v0, v0, v120
	v_or_b32_e32 v13, v14, v120
	v_mad_u64_u32 v[2:3], s[58:59], v0, s63, v[124:125]
	v_mad_u64_u32 v[8:9], s[58:59], v0, s65, v[126:127]
	v_mad_u64_u32 v[16:17], s[58:59], v13, s63, v[124:125]
	v_mad_i32_i24 v3, v1, s63, v3
	v_mad_i32_i24 v9, v1, s65, v9
	v_mad_i32_i24 v17, v15, s63, v17
	global_load_dwordx4 v[0:3], v[2:3], off sc1
	s_nop 0
	global_load_dwordx4 v[4:7], v[8:9], off offset:16
	s_nop 0
	global_load_dwordx4 v[8:11], v[8:9], off
	s_nop 0
	global_load_dwordx4 v[28:31], v[16:17], off sc1
	v_mad_u64_u32 v[16:17], s[58:59], v13, s65, v[126:127]
	v_mul_hi_i32 v13, v12, s64
	v_lshrrev_b32_e32 v14, 31, v13
	v_ashrrev_i32_e32 v13, 11, v13
	v_add_u32_e32 v13, v13, v14
	v_mul_i32_i24_e32 v14, 0x2400, v13
	v_sub_u32_e32 v12, v12, v14
	v_mad_i32_i24 v17, v15, s65, v17
	v_bfe_i32 v15, v12, 6, 16
	v_mul_i32_i24_e32 v15, 0x2aab, v15
	global_load_dwordx4 v[24:27], v[16:17], off offset:16
	global_load_dwordx4 v[32:35], v[16:17], off
	v_lshrrev_b32_e32 v16, 31, v15
	v_lshrrev_b32_e32 v15, 17, v15
	v_add_u16_e32 v15, v15, v16
	v_lshrrev_b32_e32 v14, 6, v12
	v_mul_lo_u16_e32 v15, 12, v15
	v_sub_u16_e32 v14, v14, v15
	v_lshrrev_b32_e32 v15, 2, v12
	v_and_b32_e32 v128, 3, v13
	v_bfe_i32 v14, v14, 0, 16
	v_and_b32_e32 v15, 8, v15
	v_lshlrev_b32_e32 v13, 4, v13
	v_lshl_or_b32 v14, v14, 4, v15
	v_and_b32_e32 v130, 0xffffffc0, v13
	v_ashrrev_i32_e32 v13, 31, v12
	v_ashrrev_i32_e32 v15, 31, v14
	v_ashrrev_i32_e32 v131, 31, v130
	v_lshlrev_b64 v[40:41], 4, v[12:13]
	v_lshlrev_b64 v[42:43], 2, v[14:15]
	v_lshlrev_b64 v[12:13], 2, v[130:131]
	v_lshl_add_u64 v[132:133], s[8:9], 0, v[40:41]
	v_lshl_add_u64 v[134:135], s[10:11], 0, v[42:43]
	v_or_b32_e32 v12, v12, v128
	v_mad_u64_u32 v[14:15], s[58:59], v12, s63, v[132:133]
	v_mad_u64_u32 v[16:17], s[58:59], v12, s65, v[134:135]
	v_or_b32_e32 v12, 1, v130
	v_mad_i32_i24 v15, v13, s63, v15
	v_mad_i32_i24 v17, v13, s65, v17
	v_ashrrev_i32_e32 v13, 31, v12
	v_lshlrev_b64 v[12:13], 2, v[12:13]
	v_or_b32_e32 v12, v12, v128
	v_mad_u64_u32 v[18:19], s[58:59], v12, s63, v[132:133]
	v_mad_i32_i24 v19, v13, s63, v19
	global_load_dwordx4 v[20:23], v[16:17], off
	global_load_dwordx4 v[48:51], v[18:19], off sc1
	v_mad_u64_u32 v[18:19], s[58:59], v12, s65, v[134:135]
	v_mad_i32_i24 v19, v13, s65, v19
	global_load_dwordx4 v[52:55], v[18:19], off offset:16
	global_load_dwordx4 v[60:63], v[18:19], off
	s_nop 0
	global_load_dwordx4 v[12:15], v[14:15], off sc1
	s_nop 0
	global_load_dwordx4 v[16:19], v[16:17], off offset:16
	v_mad_i64_i32 v[44:45], s[58:59], v130, s66, 0
	v_mul_hi_u32_u24_e32 v46, 0x24000, v128
	v_mul_u32_u24_e32 v47, 0x24000, v128
	v_or_b32_e32 v45, v45, v46
	v_or_b32_e32 v44, v44, v47
	v_lshl_add_u64 v[136:137], v[44:45], 0, v[40:41]
	v_mad_i64_i32 v[40:41], s[58:59], v130, s67, 0
	v_mul_hi_u32_u24_e32 v44, 0x300, v128
	v_mul_u32_u24_e32 v45, 0x300, v128
	v_or_b32_e32 v41, v41, v44
	v_or_b32_e32 v40, v40, v45
	v_lshl_add_u64 v[40:41], v[40:41], 0, v[42:43]
	v_lshl_add_u64 v[138:139], v[40:41], 0, s[34:35]
	v_mad_i64_i32 v[40:41], s[58:59], v122, s66, 0
	v_mul_hi_u32_u24_e32 v42, 0x24000, v120
	v_mul_u32_u24_e32 v43, 0x24000, v120
	v_or_b32_e32 v41, v41, v42
	v_or_b32_e32 v40, v40, v43
	v_lshl_add_u64 v[140:141], v[40:41], 0, v[36:37]
	v_mad_i64_i32 v[36:37], s[58:59], v122, s67, 0
	v_mul_hi_u32_u24_e32 v40, 0x300, v120
	v_mul_u32_u24_e32 v41, 0x300, v120
	v_or_b32_e32 v37, v37, v40
	v_or_b32_e32 v36, v36, v41
	v_lshl_add_u64 v[36:37], v[36:37], 0, v[38:39]
	v_lshl_add_u64 v[142:143], v[36:37], 0, s[34:35]
	v_mov_b32_e32 v146, 0
	s_waitcnt vmcnt(0)
	v_mov_b64_e32 v[38:39], v[30:31]
	s_mov_b32 s60, 0
	v_mov_b32_e32 v147, v146
	v_mov_b32_e32 v150, v146
	v_mov_b32_e32 v151, v146
	v_mov_b32_e32 v152, v146
	v_mov_b32_e32 v153, v146
	v_mov_b64_e32 v[42:43], v[26:27]
	v_mov_b64_e32 v[46:47], v[34:35]
	v_mov_b32_e32 v154, v146
	v_mov_b32_e32 v155, v146
	v_mov_b32_e32 v156, v146
	v_mov_b32_e32 v157, v146
	v_mov_b32_e32 v158, v146
	v_mov_b32_e32 v159, v146
	v_mov_b32_e32 v160, v146
	v_mov_b32_e32 v161, v146
	v_mov_b32_e32 v162, v146
	v_mov_b32_e32 v163, v146
	v_mov_b64_e32 v[40:41], v[24:25]
	v_mov_b64_e32 v[44:45], v[32:33]
	v_mov_b64_e32 v[36:37], v[28:29]
	v_mov_b64_e32 v[58:59], v[50:51]
	v_mov_b64_e32 v[70:71], v[54:55]
	v_mov_b64_e32 v[66:67], v[62:63]
	v_mov_b64_e32 v[56:57], v[48:49]
	v_mov_b64_e32 v[64:65], v[60:61]
	v_mov_b64_e32 v[68:69], v[52:53]
	s_branch .LBB0_549

.LBB0_549:
	v_lshl_add_u64 v[144:145], s[42:43], 0, v[140:141]
	v_add_co_u32_e32 v72, vcc, s77, v144
	v_lshl_add_u64 v[74:75], s[42:43], 0, v[142:143]
	s_nop 0
	v_addc_co_u32_e32 v73, vcc, 0, v145, vcc
	global_load_dwordx4 v[108:111], v[72:73], off sc1
	global_load_dwordx4 v[116:119], v[74:75], off offset:-3072
	v_add_co_u32_e32 v72, vcc, s78, v144
	v_lshl_add_u64 v[148:149], s[42:43], 0, v[136:137]
	s_nop 0
	v_addc_co_u32_e32 v73, vcc, 0, v145, vcc
	global_load_dwordx4 v[100:103], v[72:73], off sc1
	global_load_dwordx4 v[96:99], v[74:75], off offset:16
	global_load_dwordx4 v[112:115], v[74:75], off offset:-3056
	global_load_dwordx4 v[104:107], v[74:75], off
	v_add_co_u32_e32 v72, vcc, s77, v148
	v_lshl_add_u64 v[80:81], s[42:43], 0, v[138:139]
	s_nop 0
	v_addc_co_u32_e32 v73, vcc, 0, v149, vcc
	global_load_dwordx4 v[84:87], v[72:73], off sc1
	global_load_dwordx4 v[92:95], v[80:81], off offset:-3072
	v_add_co_u32_e32 v72, vcc, s78, v148
	v_cvt_pk_bf16_f32 v164, v146, v147
	s_nop 0
	v_addc_co_u32_e32 v73, vcc, 0, v149, vcc
	global_load_dwordx4 v[76:79], v[72:73], off sc1
	s_nop 0
	global_load_dwordx4 v[72:75], v[80:81], off offset:16
	global_load_dwordx4 v[88:91], v[80:81], off offset:-3056
	s_nop 0
	global_load_dwordx4 v[80:83], v[80:81], off
	v_add_co_u32_e32 v168, vcc, s75, v144
	v_cvt_pk_bf16_f32 v165, v150, v151
	v_cvt_pk_bf16_f32 v166, v152, v153
	v_cvt_pk_bf16_f32 v167, v154, v155
	v_addc_co_u32_e32 v169, vcc, 0, v145, vcc
	global_store_dwordx4 v[168:169], v[164:167], off sc1
	v_lshlrev_b32_e32 v168, 16, v3
	v_and_b32_e32 v169, 0xffff0000, v3
	v_lshlrev_b32_e32 v166, 16, v1
	v_and_b32_e32 v167, 0xffff0000, v1
	v_lshlrev_b32_e32 v164, 16, v0
	v_and_b32_e32 v165, 0xffff0000, v0
	v_pk_fma_f32 v[150:151], v[10:11], v[150:151], v[166:167]
	v_lshlrev_b32_e32 v166, 16, v2
	v_and_b32_e32 v167, 0xffff0000, v2
	v_pk_fma_f32 v[146:147], v[8:9], v[146:147], v[164:165]
	v_pk_fma_f32 v[152:153], v[4:5], v[152:153], v[166:167]
	v_pk_fma_f32 v[154:155], v[6:7], v[154:155], v[168:169]
	v_add_co_u32_e32 v168, vcc, s76, v144
	v_cvt_pk_bf16_f32 v164, v146, v147
	v_cvt_pk_bf16_f32 v165, v150, v151
	v_cvt_pk_bf16_f32 v166, v152, v153
	v_cvt_pk_bf16_f32 v167, v154, v155
	v_addc_co_u32_e32 v169, vcc, 0, v145, vcc
	global_store_dwordx4 v[168:169], v[164:167], off sc1
	v_add_co_u32_e32 v168, vcc, s75, v148
	s_nop 0
	v_cvt_pk_bf16_f32 v164, v156, v157
	v_cvt_pk_bf16_f32 v165, v158, v159
	v_cvt_pk_bf16_f32 v166, v160, v161
	v_cvt_pk_bf16_f32 v167, v162, v163
	v_addc_co_u32_e32 v169, vcc, 0, v149, vcc
	global_store_dwordx4 v[168:169], v[164:167], off sc1
	v_lshlrev_b32_e32 v168, 16, v15
	v_and_b32_e32 v169, 0xffff0000, v15
	v_lshlrev_b32_e32 v166, 16, v13
	v_and_b32_e32 v167, 0xffff0000, v13
	v_lshlrev_b32_e32 v164, 16, v12
	v_and_b32_e32 v165, 0xffff0000, v12
	v_pk_fma_f32 v[158:159], v[22:23], v[158:159], v[166:167]
	v_lshlrev_b32_e32 v166, 16, v14
	v_and_b32_e32 v167, 0xffff0000, v14
	v_pk_fma_f32 v[162:163], v[18:19], v[162:163], v[168:169]
	v_add_co_u32_e32 v168, vcc, 0x14894000, v148
	s_cmp_gt_u32 s60, 59
	v_pk_fma_f32 v[156:157], v[20:21], v[156:157], v[164:165]
	v_pk_fma_f32 v[160:161], v[16:17], v[160:161], v[166:167]
	v_addc_co_u32_e32 v169, vcc, 0, v149, vcc
	s_cselect_b64 s[58:59], -1, 0
	v_cvt_pk_bf16_f32 v164, v156, v157
	v_cvt_pk_bf16_f32 v165, v158, v159
	v_cvt_pk_bf16_f32 v166, v160, v161
	v_cvt_pk_bf16_f32 v167, v162, v163
	s_and_b64 vcc, exec, s[58:59]
	global_store_dwordx4 v[168:169], v[164:167], off sc1
	s_cbranch_vccnz .LBB0_548
	v_add_u32_e32 v10, s60, v122
	v_add_u32_e32 v0, 4, v10
	v_add_u32_e32 v10, 5, v10
	v_ashrrev_i32_e32 v1, 31, v0
	v_ashrrev_i32_e32 v11, 31, v10
	v_lshlrev_b64 v[0:1], 2, v[0:1]
	v_lshlrev_b64 v[12:13], 2, v[10:11]
	v_or_b32_e32 v0, v0, v120
	v_or_b32_e32 v12, v12, v120
	v_mad_u64_u32 v[2:3], s[80:81], v0, s63, v[124:125]
	v_mad_u64_u32 v[8:9], s[80:81], v0, s65, v[126:127]
	v_mad_u64_u32 v[14:15], s[80:81], v12, s63, v[124:125]
	v_mad_i32_i24 v3, v1, s63, v3
	v_mad_i32_i24 v9, v1, s65, v9
	v_mad_i32_i24 v15, v13, s63, v15
	v_add_u32_e32 v22, s60, v130
	global_load_dwordx4 v[0:3], v[2:3], off sc1
	s_nop 0
	global_load_dwordx4 v[4:7], v[8:9], off offset:16
	s_nop 0
	global_load_dwordx4 v[8:11], v[8:9], off
	s_nop 0
	global_load_dwordx4 v[36:39], v[14:15], off sc1
	v_mad_u64_u32 v[14:15], s[80:81], v12, s65, v[126:127]
	v_add_u32_e32 v12, 4, v22
	v_add_u32_e32 v22, 5, v22
	v_mad_i32_i24 v15, v13, s65, v15
	v_ashrrev_i32_e32 v13, 31, v12
	v_ashrrev_i32_e32 v23, 31, v22
	v_lshlrev_b64 v[12:13], 2, v[12:13]
	v_lshlrev_b64 v[64:65], 2, v[22:23]
	v_or_b32_e32 v12, v12, v128
	v_or_b32_e32 v64, v64, v128
	global_load_dwordx4 v[40:43], v[14:15], off offset:16
	global_load_dwordx4 v[44:47], v[14:15], off
	v_mad_u64_u32 v[14:15], s[80:81], v12, s63, v[132:133]
	v_mad_u64_u32 v[20:21], s[80:81], v12, s65, v[134:135]
	v_mad_u64_u32 v[56:57], s[80:81], v64, s63, v[132:133]
	v_mad_u64_u32 v[66:67], s[80:81], v64, s65, v[134:135]
	v_mad_i32_i24 v15, v13, s63, v15
	v_mad_i32_i24 v21, v13, s65, v21
	v_mad_i32_i24 v57, v65, s63, v57
	v_mad_i32_i24 v67, v65, s65, v67
	global_load_dwordx4 v[12:15], v[14:15], off sc1
	s_nop 0
	global_load_dwordx4 v[16:19], v[20:21], off offset:16
	s_nop 0
	global_load_dwordx4 v[20:23], v[20:21], off
	s_nop 0
	global_load_dwordx4 v[56:59], v[56:57], off sc1
	s_nop 0
	global_load_dwordx4 v[68:71], v[66:67], off offset:16
	s_nop 0
	global_load_dwordx4 v[64:67], v[66:67], off
	s_branch .LBB0_548

.LBB0_605:
	s_cmp_lt_i32 s44, 5
	s_cselect_b64 s[6:7], -1, 0
	s_and_b64 s[52:53], s[6:7], s[8:9]
	s_xor_b64 s[6:7], s[52:53], -1
	s_cmpk_gt_i32 s2, 0x3ff
	s_cselect_b64 s[8:9], -1, 0
	s_or_b64 s[6:7], s[8:9], s[6:7]
	s_and_b64 vcc, exec, s[6:7]
	s_cbranch_vccnz .LBB0_628
	s_ashr_i32 s6, s2, 8
	s_ashr_i32 s7, s6, 31
	s_lshl_b32 s3, s2, 4
	s_lshl_b64 s[6:7], s[6:7], 12
	s_and_b32 s8, s3, 0xfc0
	s_or_b32 s6, s6, s8
	s_add_u32 s65, s42, 0x14804000
	s_addc_u32 s67, s43, 0
	s_mul_i32 s8, s2, 0x24000
	s_mul_hi_i32 s9, s2, 0x24000
	s_add_u32 s8, s65, s8
	v_readfirstlane_b32 s10, v213
	s_addc_u32 s9, s67, s9
	s_lshr_b32 s10, s10, 7
	s_mulk_i32 s10, 0x900
	v_or_b32_e32 v0, s10, v228
	v_ashrrev_i32_e32 v1, 31, v0
	v_or_b32_e32 v4, 64, v0
	v_lshl_add_u64 v[2:3], v[0:1], 4, s[8:9]
	v_ashrrev_i32_e32 v5, 31, v4
	v_lshl_add_u64 v[4:5], v[4:5], 4, s[8:9]
	global_load_dwordx4 v[48:51], v[2:3], off sc1
	global_load_dwordx4 v[52:55], v[4:5], off sc1
	v_or_b32_e32 v2, 0x80, v0
	v_or_b32_e32 v0, 0xc0, v0
	v_ashrrev_i32_e32 v3, 31, v2
	v_ashrrev_i32_e32 v1, 31, v0
	v_lshl_add_u64 v[2:3], v[2:3], 4, s[8:9]
	v_lshl_add_u64 v[0:1], v[0:1], 4, s[8:9]
	s_add_i32 s11, s10, 0x100
	global_load_dwordx4 v[56:59], v[2:3], off sc1
	global_load_dwordx4 v[60:63], v[0:1], off sc1
	v_or_b32_e32 v0, s11, v228
	s_add_i32 s11, s10, 0x140
	v_ashrrev_i32_e32 v1, 31, v0
	v_or_b32_e32 v2, s11, v228
	v_lshl_add_u64 v[0:1], v[0:1], 4, s[8:9]
	v_ashrrev_i32_e32 v3, 31, v2
	s_add_i32 s11, s10, 0x180
	v_lshl_add_u64 v[2:3], v[2:3], 4, s[8:9]
	global_load_dwordx4 v[64:67], v[0:1], off sc1
	global_load_dwordx4 v[68:71], v[2:3], off sc1
	v_or_b32_e32 v0, s11, v228
	s_add_i32 s11, s10, 0x1c0
	v_ashrrev_i32_e32 v1, 31, v0
	v_or_b32_e32 v2, s11, v228
	v_lshl_add_u64 v[0:1], v[0:1], 4, s[8:9]
	v_ashrrev_i32_e32 v3, 31, v2
	s_add_i32 s11, s10, 0x200
	v_lshl_add_u64 v[2:3], v[2:3], 4, s[8:9]
	global_load_dwordx4 v[72:75], v[0:1], off sc1
	global_load_dwordx4 v[76:79], v[2:3], off sc1
	v_or_b32_e32 v0, s11, v228
	s_add_i32 s11, s10, 0x240
	v_ashrrev_i32_e32 v1, 31, v0
	v_or_b32_e32 v2, s11, v228
	v_lshl_add_u64 v[0:1], v[0:1], 4, s[8:9]
	v_ashrrev_i32_e32 v3, 31, v2
	s_add_i32 s11, s10, 0x280
	v_lshl_add_u64 v[2:3], v[2:3], 4, s[8:9]
	global_load_dwordx4 v[84:87], v[0:1], off sc1
	global_load_dwordx4 v[92:95], v[2:3], off sc1
	v_or_b32_e32 v0, s11, v228
	s_addk_i32 s10, 0x2c0
	v_ashrrev_i32_e32 v1, 31, v0
	v_or_b32_e32 v2, s10, v228
	v_lshl_add_u64 v[0:1], v[0:1], 4, s[8:9]
	v_ashrrev_i32_e32 v3, 31, v2
	s_and_b32 s10, s2, 3
	v_lshl_add_u64 v[2:3], v[2:3], 4, s[8:9]
	global_load_dwordx4 v[96:99], v[0:1], off sc1
	global_load_dwordx4 v[100:103], v[2:3], off sc1
	s_add_u32 s54, s42, 0x9004000
	v_mul_u32_u24_e32 v0, 0xaab, v213
	v_mov_b32_e32 v1, 24
	s_addc_u32 s55, s43, 0
	v_mul_lo_u16_sdwa v1, v0, v1 dst_sel:DWORD dst_unused:UNUSED_PAD src0_sel:WORD_1 src1_sel:DWORD
	v_sub_u16_e32 v4, v213, v1
	v_or_b32_sdwa v2, s6, v0 dst_sel:DWORD dst_unused:UNUSED_PAD src0_sel:DWORD src1_sel:WORD_1
	s_movk_i32 s70, 0x2200
	v_mov_b64_e32 v[0:1], s[54:55]
	v_mad_u64_u32 v[2:3], s[8:9], v2, s70, v[0:1]
	v_mov_b32_e32 v5, 0x2200
	v_mad_i32_i24 v3, s7, v5, v3
	s_mul_i32 s56, s10, 0x180
	s_mov_b32 s57, 0
	v_lshlrev_b16_e32 v4, 3, v4
	v_lshl_add_u64 v[2:3], v[2:3], 0, s[56:57]
	v_lshlrev_b32_e32 v216, 1, v4
	v_mov_b32_e32 v217, 0
	v_lshl_add_u64 v[2:3], v[2:3], 0, v[216:217]
	global_load_dwordx4 v[80:83], v[2:3], off offset:1536
	global_load_dwordx4 v[88:91], v[2:3], off
	v_add_u16_e32 v2, 0x200, v213
	v_mul_u32_u24_e32 v3, 0xaab, v2
	v_lshrrev_b32_e32 v216, 16, v3
	v_mul_lo_u16_e32 v3, 24, v216
	v_sub_u16_e32 v6, v2, v3
	v_lshl_add_u64 v[2:3], s[6:7], 0, v[216:217]
	v_mad_u64_u32 v[4:5], s[8:9], v2, s70, v[0:1]
	v_mad_i32_i24 v5, v3, s70, v5
	v_lshl_add_u64 v[2:3], v[4:5], 0, s[56:57]
	v_lshlrev_b16_e32 v4, 3, v6
	v_lshlrev_b32_e32 v216, 1, v4
	v_lshl_add_u64 v[2:3], v[2:3], 0, v[216:217]
	s_movk_i32 s11, 0xaab
	global_load_dwordx4 v[104:107], v[2:3], off offset:1536
	global_load_dwordx4 v[108:111], v[2:3], off
	v_or_b32_e32 v2, 0x400, v213
	v_mul_u32_u24_sdwa v3, v2, s11 dst_sel:DWORD dst_unused:UNUSED_PAD src0_sel:WORD_0 src1_sel:DWORD
	v_lshrrev_b32_e32 v216, 16, v3
	v_mul_lo_u16_e32 v3, 24, v216
	v_sub_u16_e32 v4, v2, v3
	v_lshl_add_u64 v[2:3], s[6:7], 0, v[216:217]
	v_mad_u64_u32 v[0:1], s[6:7], v2, s70, v[0:1]
	v_mad_i32_i24 v1, v3, s70, v1
	v_lshlrev_b16_e32 v2, 3, v4
	v_lshl_add_u64 v[0:1], v[0:1], 0, s[56:57]
	v_lshlrev_b32_e32 v216, 1, v2
	v_lshl_add_u64 v[0:1], v[0:1], 0, v[216:217]
	global_load_dwordx4 v[112:115], v[0:1], off offset:1536
	global_load_dwordx4 v[116:119], v[0:1], off
	s_add_u32 s58, s42, 0x11804000
	s_addc_u32 s59, s43, 0
	s_add_u32 s71, s42, 0x5004000
	v_mbcnt_lo_u32_b32 v0, -1, 0
	s_addc_u32 s72, s43, 0
	s_lshl_b32 s73, s46, 4
	s_mov_b32 s74, 0x2aaaaaab
	s_movk_i32 s75, 0x190
	s_movk_i32 s76, 0x310
	s_mov_b64 s[60:61], 0x100000
	s_mov_b32 s77, 0x100000
	s_mov_b64 s[62:63], 0x200000
	s_mov_b32 s78, 0x200000
	v_mbcnt_hi_u32_b32 v229, -1, v0
	s_movk_i32 s79, 0x30c
	s_mov_b32 s80, 0x9004000
	s_mov_b32 s64, 0x3b2aaaab
	s_mov_b32 s66, 0x358637bd
	s_mov_b32 s81, 0x800000
	s_mov_b32 s82, s2
	s_branch .LBB0_608
.LBB0_607:
	s_or_b64 exec, exec, s[6:7]
	s_waitcnt lgkmcnt(0)
	v_ashrrev_i32_e32 v0, 3, v237
	v_add_u32_e32 v0, v0, v238
	v_mul_lo_u32 v1, v0, 48
	v_sub_u32_e32 v12, v230, v1
	v_ashrrev_i32_e32 v1, 31, v0
	v_lshl_add_u64 v[10:11], s[12:13], 0, v[0:1]
	v_mov_b64_e32 v[8:9], s[42:43]
	v_mad_u64_u32 v[4:5], s[6:7], v10, s70, v[8:9]
	v_mov_b32_e32 v6, v5
	v_lshlrev_b32_e32 v2, 3, v12
	v_mad_u64_u32 v[6:7], s[6:7], v11, s70, v[6:7]
	s_mul_i32 s56, s16, 0x300
	v_mov_b32_e32 v5, v6
	v_ashrrev_i32_e32 v3, 31, v2
	v_lshl_add_u64 v[4:5], v[4:5], 0, s[56:57]
	v_lshlrev_b64 v[16:17], 1, v[2:3]
	v_lshl_add_u64 v[4:5], v[4:5], 0, v[16:17]
	v_add_co_u32_e32 v4, vcc, s80, v4
	s_nop 1
	v_addc_co_u32_e32 v5, vcc, 0, v5, vcc
	s_barrier
	global_load_dwordx4 v[22:25], v[4:5], off offset:3072 sc1
	v_lshl_add_u32 v1, v0, 2, 0
	v_mul_lo_u32 v0, v0, s79
	v_lshlrev_b32_e32 v4, 4, v12
	v_add3_u32 v0, v1, v0, v4
	s_load_dwordx2 s[18:19], s[0:1], 0x38
	ds_read_b128 v[26:29], v0 offset:63488
	ds_read2st64_b32 v[18:19], v1 offset0:16 offset1:17
	ds_read2st64_b32 v[14:15], v1 offset0:18 offset1:19
	s_add_u32 s16, s71, s56
	s_addc_u32 s17, s72, 0
	s_waitcnt lgkmcnt(0)
	v_lshlrev_b32_e32 v12, 16, v26
	v_and_b32_e32 v13, 0xffff0000, v26
	v_lshlrev_b32_e32 v20, 16, v27
	v_and_b32_e32 v21, 0xffff0000, v27
	v_lshl_add_u64 v[4:5], v[2:3], 2, s[18:19]
	global_load_dwordx4 v[0:3], v[4:5], off offset:16
	s_nop 0
	global_load_dwordx4 v[4:7], v[4:5], off
	v_lshlrev_b64 v[10:11], 12, v[10:11]
	v_lshl_add_u64 v[10:11], s[16:17], 0, v[10:11]
	v_lshl_add_u64 v[16:17], v[10:11], 0, v[16:17]
	s_add_i32 s3, s3, s73
	s_waitcnt vmcnt(2)
	v_lshlrev_b32_e32 v30, 16, v22
	v_and_b32_e32 v31, 0xffff0000, v22
	v_lshlrev_b32_e32 v32, 16, v23
	v_and_b32_e32 v33, 0xffff0000, v23
	v_mul_f32_e32 v22, 0xbfb8aa3b, v30
	v_mul_f32_e32 v23, 0xbfb8aa3b, v31
	v_exp_f32_e32 v22, v22
	v_exp_f32_e32 v23, v23
	v_mul_f32_e32 v26, 0xbfb8aa3b, v32
	v_mul_f32_e32 v27, 0xbfb8aa3b, v33
	v_exp_f32_e32 v26, v26
	v_exp_f32_e32 v27, v27
	v_pk_add_f32 v[22:23], v[22:23], 1.0 op_sel_hi:[1,0]
	v_lshlrev_b32_e32 v34, 16, v24
	v_div_scale_f32 v36, s[6:7], v23, v23, v31
	v_pk_add_f32 v[26:27], v[26:27], 1.0 op_sel_hi:[1,0]
	v_div_scale_f32 v38, s[6:7], v22, v22, v30
	v_rcp_f32_e32 v44, v36
	v_div_scale_f32 v40, s[8:9], v27, v27, v33
	v_rcp_f32_e32 v45, v38
	v_rcp_f32_e32 v46, v40
	v_fma_f32 v120, -v36, v44, 1.0
	v_div_scale_f32 v37, vcc, v31, v23, v31
	v_fma_f32 v121, -v38, v45, 1.0
	v_fmac_f32_e32 v44, v120, v44
	v_div_scale_f32 v39, s[6:7], v30, v22, v30
	v_fma_f32 v122, -v40, v46, 1.0
	v_fmac_f32_e32 v45, v121, v45
	v_mul_f32_e32 v120, v37, v44
	v_div_scale_f32 v41, s[8:9], v33, v27, v33
	v_fmac_f32_e32 v46, v122, v46
	v_mul_f32_e32 v121, v39, v45
	v_fma_f32 v124, -v36, v120, v37
	v_mul_f32_e32 v122, v41, v46
	v_fma_f32 v125, -v38, v121, v39
	v_fmac_f32_e32 v120, v124, v44
	v_fma_f32 v126, -v40, v122, v41
	v_fmac_f32_e32 v121, v125, v45
	v_fmac_f32_e32 v122, v126, v46
	s_mov_b64 vcc, s[6:7]
	v_and_b32_e32 v24, 0xffff0000, v24
	v_div_scale_f32 v42, s[10:11], v26, v26, v32
	v_rcp_f32_e32 v36, v23
	s_nop 0
	v_mul_f32_e32 v23, v31, v36
	s_mov_b64 vcc, s[8:9]
	v_mul_f32_e32 v35, 0xbfb8aa3b, v34
	v_rcp_f32_e32 v47, v42
	v_rcp_f32_e32 v31, v22
	s_nop 0
	v_mul_f32_e32 v22, v30, v31
	v_mul_f32_e32 v31, 0xbfb8aa3b, v24
	v_rcp_f32_e32 v30, v27
	s_nop 0
	v_mul_f32_e32 v27, v33, v30
	v_exp_f32_e32 v30, v35
	v_exp_f32_e32 v31, v31
	v_fma_f32 v123, -v42, v47, 1.0
	v_div_scale_f32 v43, s[10:11], v32, v26, v32
	v_fmac_f32_e32 v47, v123, v47
	v_pk_add_f32 v[30:31], v[30:31], 1.0 op_sel_hi:[1,0]
	v_mul_f32_e32 v123, v43, v47
	v_fma_f32 v127, -v42, v123, v43
	v_fmac_f32_e32 v123, v127, v47
	s_mov_b64 vcc, s[10:11]
	v_rcp_f32_e32 v33, v26
	s_nop 0
	v_mul_f32_e32 v26, v32, v33
	v_lshlrev_b32_e32 v32, 16, v28
	v_and_b32_e32 v33, 0xffff0000, v28
	v_rcp_f32_e32 v28, v31
	s_nop 0
	v_mul_f32_e32 v31, v24, v28
	v_lshlrev_b32_e32 v37, 16, v25
	v_and_b32_e32 v39, 0xffff0000, v25
	v_mul_f32_e32 v24, 0xbfb8aa3b, v37
	v_mul_f32_e32 v25, 0xbfb8aa3b, v39
	v_exp_f32_e32 v24, v24
	v_exp_f32_e32 v25, v25
	v_rcp_f32_e32 v28, v30
	s_nop 0
	v_mul_f32_e32 v30, v34, v28
	v_pk_add_f32 v[24:25], v[24:25], 1.0 op_sel_hi:[1,0]
	v_lshlrev_b32_e32 v28, 16, v29
	v_and_b32_e32 v29, 0xffff0000, v29
	v_rcp_f32_e32 v34, v25
	s_nop 0
	v_mul_f32_e32 v25, v39, v34
	v_mov_b32_e32 v39, v18
	v_div_scale_f32 v34, vcc, v37, v24, v37
	v_rcp_f32_e32 v34, v24
	s_nop 0
	v_mul_f32_e32 v24, v37, v34
	v_ashrrev_i32_e32 v34, 3, v235
	v_add_u32_e32 v34, v34, v236
	v_lshl_add_u32 v40, v34, 2, 0
	ds_read2st64_b32 v[36:37], v40 offset0:16 offset1:17
	ds_read2st64_b32 v[10:11], v40 offset0:18 offset1:19
	v_mul_lo_u32 v35, v34, 48
	s_waitcnt lgkmcnt(1)
	v_mov_b32_e32 v38, v36
	v_mov_b32_e32 v18, v37
	v_pk_add_f32 v[18:19], v[38:39], v[18:19]
	s_waitcnt lgkmcnt(0)
	v_mov_b32_e32 v36, v10
	v_mov_b32_e32 v37, v14
	v_pk_add_f32 v[18:19], v[18:19], v[36:37]
	v_mov_b32_e32 v14, v11
	v_pk_add_f32 v[14:15], v[18:19], v[14:15]
	v_mov_b64_e32 v[10:11], s[66:67]
	v_pk_fma_f32 v[36:37], v[14:15], s[64:65], v[10:11] op_sel_hi:[1,0,0]
	s_nop 0
	v_mul_f32_e32 v14, 0x4b800000, v37
	v_cmp_gt_f32_e32 vcc, s81, v37
	s_nop 1
	v_cndmask_b32_e32 v14, v37, v14, vcc
	v_rsq_f32_e32 v15, v14
	v_sub_u32_e32 v37, v234, v35
	v_ashrrev_i32_e32 v35, 31, v34
	v_lshlrev_b32_e32 v14, 3, v37
	v_mul_f32_e32 v18, 0x45800000, v15
	v_cndmask_b32_e32 v18, v15, v18, vcc
	v_pk_mul_f32 v[12:13], v[18:19], v[12:13] op_sel_hi:[0,1]
	s_waitcnt vmcnt(0)
	v_pk_mul_f32 v[4:5], v[4:5], v[12:13]
	v_pk_mul_f32 v[12:13], v[18:19], v[20:21] op_sel_hi:[0,1]
	v_pk_mul_f32 v[6:7], v[6:7], v[12:13]
	v_pk_mul_f32 v[4:5], v[22:23], v[4:5]
	v_pk_mul_f32 v[6:7], v[26:27], v[6:7]
	v_cvt_pk_bf16_f32 v4, v4, v5
	v_cvt_pk_bf16_f32 v5, v6, v7
	v_pk_mul_f32 v[6:7], v[18:19], v[32:33] op_sel_hi:[0,1]
	v_pk_mul_f32 v[0:1], v[0:1], v[6:7]
	v_ashrrev_i32_e32 v15, 31, v14
	v_pk_mul_f32 v[0:1], v[30:31], v[0:1]
	v_mul_f32_e32 v20, 0x4b800000, v36
	v_cvt_pk_bf16_f32 v6, v0, v1
	v_pk_mul_f32 v[0:1], v[18:19], v[28:29] op_sel_hi:[0,1]
	v_pk_mul_f32 v[0:1], v[2:3], v[0:1]
	v_lshlrev_b32_e32 v21, 4, v37
	v_pk_mul_f32 v[0:1], v[24:25], v[0:1]
	s_nop 0
	v_cvt_pk_bf16_f32 v7, v0, v1
	v_lshl_add_u64 v[0:1], s[12:13], 0, v[34:35]
	v_mad_u64_u32 v[2:3], s[6:7], v0, s70, v[8:9]
	global_store_dwordx4 v[16:17], v[4:7], off sc1
	v_lshl_add_u64 v[16:17], v[14:15], 2, s[18:19]
	s_nop 0
	v_mov_b32_e32 v4, v3
	v_mad_u64_u32 v[4:5], s[6:7], v1, s70, v[4:5]
	v_mov_b32_e32 v3, v4
	v_lshl_add_u64 v[2:3], v[2:3], 0, s[56:57]
	v_lshlrev_b64 v[6:7], 1, v[14:15]
	v_lshl_add_u64 v[2:3], v[2:3], 0, v[6:7]
	v_add_co_u32_e32 v2, vcc, s80, v2
	v_lshlrev_b64 v[0:1], 12, v[0:1]
	s_nop 0
	v_addc_co_u32_e32 v3, vcc, 0, v3, vcc
	global_load_dwordx4 v[2:5], v[2:3], off offset:3072 sc1
	s_nop 0
	global_load_dwordx4 v[12:15], v[16:17], off
	s_nop 0
	global_load_dwordx4 v[16:19], v[16:17], off offset:16
	v_cmp_gt_f32_e32 vcc, s81, v36
	v_lshl_add_u64 v[0:1], s[16:17], 0, v[0:1]
	v_lshl_add_u64 v[0:1], v[0:1], 0, v[6:7]
	v_cndmask_b32_e32 v20, v36, v20, vcc
	v_rsq_f32_e32 v26, v20
	v_mul_lo_u32 v20, v34, s79
	v_add3_u32 v20, v40, v20, v21
	ds_read_b128 v[20:23], v20 offset:63488
	v_mul_f32_e32 v28, 0x45800000, v26
	v_cndmask_b32_e32 v26, v26, v28, vcc
	s_waitcnt lgkmcnt(0)
	v_lshlrev_b32_e32 v28, 16, v20
	v_and_b32_e32 v29, 0xffff0000, v20
	s_waitcnt vmcnt(2)
	v_lshlrev_b32_e32 v27, 16, v2
	v_and_b32_e32 v2, 0xffff0000, v2
	v_mul_f32_e32 v24, 0xbfb8aa3b, v27
	v_mul_f32_e32 v25, 0xbfb8aa3b, v2
	v_exp_f32_e32 v24, v24
	v_exp_f32_e32 v25, v25
	v_pk_mul_f32 v[28:29], v[26:27], v[28:29] op_sel_hi:[0,1]
	s_waitcnt vmcnt(1)
	v_pk_mul_f32 v[12:13], v[12:13], v[28:29]
	v_pk_add_f32 v[24:25], v[24:25], 1.0 op_sel_hi:[1,0]
	s_nop 0
	s_nop 0
	v_rcp_f32_e32 v20, v25
	s_nop 0
	v_mul_f32_e32 v25, v2, v20
	v_lshlrev_b32_e32 v20, 16, v3
	v_rcp_f32_e32 v2, v24
	s_nop 0
	v_mul_f32_e32 v24, v27, v2
	v_and_b32_e32 v27, 0xffff0000, v3
	v_mul_f32_e32 v2, 0xbfb8aa3b, v20
	v_exp_f32_e32 v28, v2
	v_mul_f32_e32 v2, 0xbfb8aa3b, v27
	v_exp_f32_e32 v29, v2
	v_pk_mul_f32 v[2:3], v[24:25], v[12:13]
	v_lshlrev_b32_e32 v12, 16, v21
	v_cvt_pk_bf16_f32 v2, v2, v3
	v_pk_add_f32 v[24:25], v[28:29], 1.0 op_sel_hi:[1,0]
	v_and_b32_e32 v13, 0xffff0000, v21
	v_pk_mul_f32 v[12:13], v[26:27], v[12:13] op_sel_hi:[0,1]
	v_pk_mul_f32 v[12:13], v[14:15], v[12:13]
	v_div_scale_f32 v14, s[6:7], v24, v24, v20
	v_rcp_f32_e32 v21, v14
	v_rcp_f32_e32 v3, v25
	s_nop 0
	v_mul_f32_e32 v15, v27, v3
	v_fma_f32 v3, -v14, v21, 1.0
	v_fmac_f32_e32 v21, v3, v21
	v_div_scale_f32 v3, vcc, v20, v24, v20
	v_mul_f32_e32 v25, v3, v21
	v_fma_f32 v27, -v14, v25, v3
	v_rcp_f32_e32 v3, v24
	s_nop 0
	v_mul_f32_e32 v14, v20, v3
	v_lshlrev_b32_e32 v24, 16, v4
	v_and_b32_e32 v4, 0xffff0000, v4
	v_mul_f32_e32 v3, 0xbfb8aa3b, v24
	v_exp_f32_e32 v20, v3
	v_mul_f32_e32 v3, 0xbfb8aa3b, v4
	v_exp_f32_e32 v21, v3
	v_pk_mul_f32 v[12:13], v[14:15], v[12:13]
	v_pk_add_f32 v[14:15], v[20:21], 1.0 op_sel_hi:[1,0]
	s_nop 0
	v_cvt_pk_bf16_f32 v3, v12, v13
	v_lshlrev_b32_e32 v12, 16, v22
	v_and_b32_e32 v13, 0xffff0000, v22
	v_pk_mul_f32 v[12:13], v[26:27], v[12:13] op_sel_hi:[0,1]
	s_waitcnt vmcnt(0)
	v_pk_mul_f32 v[12:13], v[16:17], v[12:13]
	v_rcp_f32_e32 v16, v15
	s_nop 0
	v_mul_f32_e32 v15, v4, v16
	v_and_b32_e32 v21, 0xffff0000, v5
	v_lshlrev_b32_e32 v20, 16, v5
	v_rcp_f32_e32 v4, v14
	s_nop 0
	v_mul_f32_e32 v14, v24, v4
	v_mul_f32_e32 v4, 0xbfb8aa3b, v20
	v_exp_f32_e32 v16, v4
	v_mul_f32_e32 v4, 0xbfb8aa3b, v21
	v_exp_f32_e32 v17, v4
	v_pk_mul_f32 v[4:5], v[14:15], v[12:13]
	v_lshlrev_b32_e32 v12, 16, v23
	v_cvt_pk_bf16_f32 v4, v4, v5
	v_pk_add_f32 v[14:15], v[16:17], 1.0 op_sel_hi:[1,0]
	v_and_b32_e32 v13, 0xffff0000, v23
	v_pk_mul_f32 v[12:13], v[26:27], v[12:13] op_sel_hi:[0,1]
	v_pk_mul_f32 v[12:13], v[18:19], v[12:13]
	v_rcp_f32_e32 v5, v15
	s_nop 0
	v_mul_f32_e32 v15, v21, v5
	v_rcp_f32_e32 v5, v14
	s_nop 0
	v_mul_f32_e32 v14, v20, v5
	v_pk_mul_f32 v[12:13], v[14:15], v[12:13]
	s_nop 0
	v_cvt_pk_bf16_f32 v5, v12, v13
	global_store_dwordx4 v[0:1], v[2:5], off sc1
	v_ashrrev_i32_e32 v0, 3, v232
	v_add_u32_e32 v0, v0, v233
	v_mul_lo_u32 v1, v0, 48
	v_sub_u32_e32 v12, v231, v1
	v_ashrrev_i32_e32 v1, 31, v0
	v_lshl_add_u64 v[20:21], s[12:13], 0, v[0:1]
	v_mad_u64_u32 v[4:5], s[6:7], v20, s70, v[8:9]
	v_mov_b32_e32 v6, v5
	v_lshlrev_b32_e32 v2, 3, v12
	v_mad_u64_u32 v[6:7], s[6:7], v21, s70, v[6:7]
	v_mov_b32_e32 v5, v6
	v_ashrrev_i32_e32 v3, 31, v2
	v_lshl_add_u64 v[4:5], v[4:5], 0, s[56:57]
	v_lshlrev_b64 v[22:23], 1, v[2:3]
	v_lshl_add_u64 v[4:5], v[4:5], 0, v[22:23]
	v_add_co_u32_e32 v4, vcc, s80, v4
	v_lshl_add_u32 v13, v0, 2, 0
	s_nop 0
	v_addc_co_u32_e32 v5, vcc, 0, v5, vcc
	global_load_dwordx4 v[4:7], v[4:5], off offset:3072 sc1
	v_mul_lo_u32 v14, v0, s79
	v_lshlrev_b32_e32 v12, 4, v12
	v_add3_u32 v12, v13, v14, v12
	ds_read2st64_b32 v[24:25], v13 offset0:16 offset1:17
	ds_read2st64_b32 v[26:27], v13 offset0:18 offset1:19
	ds_read_b128 v[12:15], v12 offset:63488
	v_lshl_add_u64 v[16:17], v[2:3], 2, s[18:19]
	s_waitcnt lgkmcnt(0)
	v_lshlrev_b32_e32 v30, 16, v12
	v_and_b32_e32 v31, 0xffff0000, v12
	s_waitcnt vmcnt(0)
	v_lshlrev_b32_e32 v32, 16, v4
	v_and_b32_e32 v4, 0xffff0000, v4
	v_mul_f32_e32 v0, 0xbfb8aa3b, v32
	v_mul_f32_e32 v1, 0xbfb8aa3b, v4
	v_exp_f32_e32 v0, v0
	v_exp_f32_e32 v1, v1
	v_lshlrev_b32_e32 v37, 16, v5
	v_lshlrev_b32_e32 v40, 16, v6
	v_and_b32_e32 v6, 0xffff0000, v6
	v_pk_add_f32 v[28:29], v[0:1], 1.0 op_sel_hi:[1,0]
	global_load_dwordx4 v[0:3], v[16:17], off offset:16
	s_nop 0
	global_load_dwordx4 v[16:19], v[16:17], off
	v_lshlrev_b32_e32 v41, 16, v7
	v_and_b32_e32 v7, 0xffff0000, v7
	v_rcp_f32_e32 v12, v29
	s_nop 0
	v_mul_f32_e32 v29, v4, v12
	v_and_b32_e32 v35, 0xffff0000, v5
	v_mul_f32_e32 v4, 0xbfb8aa3b, v37
	v_mul_f32_e32 v5, 0xbfb8aa3b, v35
	v_exp_f32_e32 v4, v4
	v_exp_f32_e32 v5, v5
	v_rcp_f32_e32 v12, v28
	s_nop 0
	v_mul_f32_e32 v28, v32, v12
	v_pk_add_f32 v[4:5], v[4:5], 1.0 op_sel_hi:[1,0]
	v_lshlrev_b32_e32 v12, 16, v13
	v_and_b32_e32 v13, 0xffff0000, v13
	v_rcp_f32_e32 v32, v5
	s_nop 0
	v_mul_f32_e32 v33, v35, v32
	v_mul_f32_e32 v34, 0xbfb8aa3b, v40
	v_mul_f32_e32 v35, 0xbfb8aa3b, v6
	v_exp_f32_e32 v34, v34
	v_exp_f32_e32 v35, v35
	v_rcp_f32_e32 v5, v4
	s_nop 0
	v_mul_f32_e32 v32, v37, v5
	v_pk_add_f32 v[34:35], v[34:35], 1.0 op_sel_hi:[1,0]
	v_lshlrev_b32_e32 v36, 16, v14
	v_and_b32_e32 v37, 0xffff0000, v14
	v_rcp_f32_e32 v4, v35
	s_nop 0
	v_mul_f32_e32 v35, v6, v4
	v_mul_f32_e32 v4, 0xbfb8aa3b, v41
	v_mul_f32_e32 v5, 0xbfb8aa3b, v7
	v_exp_f32_e32 v4, v4
	v_exp_f32_e32 v5, v5
	v_rcp_f32_e32 v6, v34
	s_nop 0
	v_mul_f32_e32 v34, v40, v6
	v_pk_add_f32 v[4:5], v[4:5], 1.0 op_sel_hi:[1,0]
	v_lshlrev_b32_e32 v14, 16, v15
	v_and_b32_e32 v15, 0xffff0000, v15
	v_rcp_f32_e32 v6, v5
	s_nop 0
	v_mul_f32_e32 v39, v7, v6
	v_div_scale_f32 v5, vcc, v41, v4, v41
	v_rcp_f32_e32 v5, v4
	s_nop 0
	v_mul_f32_e32 v38, v41, v5
	v_lshlrev_b64 v[4:5], 12, v[20:21]
	v_add_u32_e32 v21, 0x600, v230
	v_mul_hi_i32 v6, v21, s74
	v_lshrrev_b32_e32 v7, 31, v6
	v_ashrrev_i32_e32 v6, 3, v6
	v_add_u32_e32 v20, v6, v7
	v_lshl_add_u32 v42, v20, 2, 0
	ds_read2st64_b32 v[6:7], v42 offset0:16 offset1:17
	v_lshl_add_u64 v[4:5], s[16:17], 0, v[4:5]
	v_lshl_add_u64 v[22:23], v[4:5], 0, v[22:23]
	ds_read2st64_b32 v[4:5], v42 offset0:18 offset1:19
	v_mov_b32_e32 v41, v24
	s_waitcnt lgkmcnt(1)
	v_mov_b32_e32 v40, v6
	v_mov_b32_e32 v24, v7
	v_pk_add_f32 v[6:7], v[40:41], v[24:25]
	s_waitcnt lgkmcnt(0)
	v_mov_b32_e32 v24, v4
	v_mov_b32_e32 v25, v26
	v_pk_add_f32 v[6:7], v[6:7], v[24:25]
	v_mov_b32_e32 v26, v5
	v_pk_add_f32 v[4:5], v[6:7], v[26:27]
	v_mul_lo_u32 v43, v20, 48
	v_pk_fma_f32 v[24:25], v[4:5], s[64:65], v[10:11] op_sel_hi:[1,0,0]
	s_nop 0
	v_mul_f32_e32 v4, 0x4b800000, v25
	v_cmp_gt_f32_e32 vcc, s81, v25
	s_nop 1
	v_cndmask_b32_e32 v4, v25, v4, vcc
	v_rsq_f32_e32 v4, v4
	v_sub_u32_e32 v25, v21, v43
	v_ashrrev_i32_e32 v21, 31, v20
	v_lshlrev_b32_e32 v26, 3, v25
	v_mul_f32_e32 v5, 0x45800000, v4
	v_cndmask_b32_e32 v40, v4, v5, vcc
	v_pk_mul_f32 v[4:5], v[40:41], v[30:31] op_sel_hi:[0,1]
	v_pk_mul_f32 v[6:7], v[40:41], v[12:13] op_sel_hi:[0,1]
	s_waitcnt vmcnt(0)
	v_pk_mul_f32 v[4:5], v[16:17], v[4:5]
	v_pk_mul_f32 v[6:7], v[18:19], v[6:7]
	v_pk_mul_f32 v[4:5], v[28:29], v[4:5]
	v_pk_mul_f32 v[6:7], v[32:33], v[6:7]
	v_cvt_pk_bf16_f32 v4, v4, v5
	v_cvt_pk_bf16_f32 v5, v6, v7
	v_pk_mul_f32 v[6:7], v[40:41], v[36:37] op_sel_hi:[0,1]
	v_pk_mul_f32 v[0:1], v[0:1], v[6:7]
	v_ashrrev_i32_e32 v27, 31, v26
	v_pk_mul_f32 v[0:1], v[34:35], v[0:1]
	v_lshl_add_u64 v[16:17], v[26:27], 2, s[18:19]
	v_cvt_pk_bf16_f32 v6, v0, v1
	v_pk_mul_f32 v[0:1], v[40:41], v[14:15] op_sel_hi:[0,1]
	v_pk_mul_f32 v[0:1], v[2:3], v[0:1]
	s_nop 0
	v_pk_mul_f32 v[0:1], v[38:39], v[0:1]
	s_nop 0
	v_cvt_pk_bf16_f32 v7, v0, v1
	v_lshl_add_u64 v[0:1], s[12:13], 0, v[20:21]
	v_mad_u64_u32 v[2:3], s[6:7], v0, s70, v[8:9]
	global_store_dwordx4 v[22:23], v[4:7], off sc1
	v_mul_f32_e32 v21, 0x4b800000, v24
	v_mul_lo_u32 v20, v20, s79
	v_mov_b32_e32 v4, v3
	v_mad_u64_u32 v[4:5], s[6:7], v1, s70, v[4:5]
	v_mov_b32_e32 v3, v4
	v_lshl_add_u64 v[2:3], v[2:3], 0, s[56:57]
	v_lshlrev_b64 v[6:7], 1, v[26:27]
	v_lshl_add_u64 v[2:3], v[2:3], 0, v[6:7]
	v_add_co_u32_e32 v2, vcc, s80, v2
	v_lshlrev_b64 v[0:1], 12, v[0:1]
	s_nop 0
	v_addc_co_u32_e32 v3, vcc, 0, v3, vcc
	global_load_dwordx4 v[2:5], v[2:3], off offset:3072 sc1
	s_nop 0
	global_load_dwordx4 v[12:15], v[16:17], off
	s_nop 0
	global_load_dwordx4 v[16:19], v[16:17], off offset:16
	v_cmp_gt_f32_e32 vcc, s81, v24
	v_lshl_add_u64 v[0:1], s[16:17], 0, v[0:1]
	v_lshl_add_u64 v[0:1], v[0:1], 0, v[6:7]
	v_cndmask_b32_e32 v21, v24, v21, vcc
	v_rsq_f32_e32 v26, v21
	v_lshlrev_b32_e32 v21, 4, v25
	v_add3_u32 v20, v42, v20, v21
	ds_read_b128 v[20:23], v20 offset:63488
	v_mul_f32_e32 v28, 0x45800000, v26
	v_cndmask_b32_e32 v26, v26, v28, vcc
	s_waitcnt lgkmcnt(0)
	v_lshlrev_b32_e32 v28, 16, v20
	v_and_b32_e32 v29, 0xffff0000, v20
	s_waitcnt vmcnt(2)
	v_lshlrev_b32_e32 v27, 16, v2
	v_and_b32_e32 v2, 0xffff0000, v2
	v_mul_f32_e32 v24, 0xbfb8aa3b, v27
	v_mul_f32_e32 v25, 0xbfb8aa3b, v2
	v_exp_f32_e32 v24, v24
	v_exp_f32_e32 v25, v25
	v_pk_mul_f32 v[28:29], v[26:27], v[28:29] op_sel_hi:[0,1]
	s_waitcnt vmcnt(1)
	v_pk_mul_f32 v[12:13], v[12:13], v[28:29]
	v_pk_add_f32 v[24:25], v[24:25], 1.0 op_sel_hi:[1,0]
	s_nop 0
	s_nop 0
	v_rcp_f32_e32 v20, v25
	s_nop 0
	v_mul_f32_e32 v25, v2, v20
	v_lshlrev_b32_e32 v20, 16, v3
	v_rcp_f32_e32 v2, v24
	s_nop 0
	v_mul_f32_e32 v24, v27, v2
	v_and_b32_e32 v27, 0xffff0000, v3
	v_mul_f32_e32 v2, 0xbfb8aa3b, v20
	v_exp_f32_e32 v28, v2
	v_mul_f32_e32 v2, 0xbfb8aa3b, v27
	v_exp_f32_e32 v29, v2
	v_pk_mul_f32 v[2:3], v[24:25], v[12:13]
	v_lshlrev_b32_e32 v12, 16, v21
	v_cvt_pk_bf16_f32 v2, v2, v3
	v_pk_add_f32 v[24:25], v[28:29], 1.0 op_sel_hi:[1,0]
	v_and_b32_e32 v13, 0xffff0000, v21
	v_pk_mul_f32 v[12:13], v[26:27], v[12:13] op_sel_hi:[0,1]
	v_pk_mul_f32 v[12:13], v[14:15], v[12:13]
	v_div_scale_f32 v14, s[6:7], v24, v24, v20
	v_rcp_f32_e32 v21, v14
	v_rcp_f32_e32 v3, v25
	s_nop 0
	v_mul_f32_e32 v15, v27, v3
	v_fma_f32 v3, -v14, v21, 1.0
	v_fmac_f32_e32 v21, v3, v21
	v_div_scale_f32 v3, vcc, v20, v24, v20
	v_mul_f32_e32 v25, v3, v21
	v_fma_f32 v27, -v14, v25, v3
	v_rcp_f32_e32 v3, v24
	s_nop 0
	v_mul_f32_e32 v14, v20, v3
	v_lshlrev_b32_e32 v24, 16, v4
	v_and_b32_e32 v4, 0xffff0000, v4
	v_mul_f32_e32 v3, 0xbfb8aa3b, v24
	v_exp_f32_e32 v20, v3
	v_mul_f32_e32 v3, 0xbfb8aa3b, v4
	v_exp_f32_e32 v21, v3
	v_pk_mul_f32 v[12:13], v[14:15], v[12:13]
	v_pk_add_f32 v[14:15], v[20:21], 1.0 op_sel_hi:[1,0]
	s_nop 0
	v_cvt_pk_bf16_f32 v3, v12, v13
	v_lshlrev_b32_e32 v12, 16, v22
	v_and_b32_e32 v13, 0xffff0000, v22
	v_pk_mul_f32 v[12:13], v[26:27], v[12:13] op_sel_hi:[0,1]
	s_waitcnt vmcnt(0)
	v_pk_mul_f32 v[12:13], v[16:17], v[12:13]
	v_rcp_f32_e32 v16, v15
	s_nop 0
	v_mul_f32_e32 v15, v4, v16
	v_and_b32_e32 v21, 0xffff0000, v5
	v_lshlrev_b32_e32 v20, 16, v5
	v_rcp_f32_e32 v4, v14
	s_nop 0
	v_mul_f32_e32 v14, v24, v4
	v_mul_f32_e32 v4, 0xbfb8aa3b, v20
	v_exp_f32_e32 v16, v4
	v_mul_f32_e32 v4, 0xbfb8aa3b, v21
	v_exp_f32_e32 v17, v4
	v_pk_mul_f32 v[4:5], v[14:15], v[12:13]
	v_lshlrev_b32_e32 v12, 16, v23
	v_cvt_pk_bf16_f32 v4, v4, v5
	v_pk_add_f32 v[14:15], v[16:17], 1.0 op_sel_hi:[1,0]
	v_and_b32_e32 v13, 0xffff0000, v23
	v_pk_mul_f32 v[12:13], v[26:27], v[12:13] op_sel_hi:[0,1]
	v_pk_mul_f32 v[12:13], v[18:19], v[12:13]
	v_rcp_f32_e32 v5, v15
	s_nop 0
	v_mul_f32_e32 v15, v21, v5
	v_rcp_f32_e32 v5, v14
	s_nop 0
	v_mul_f32_e32 v14, v20, v5
	v_pk_mul_f32 v[12:13], v[14:15], v[12:13]
	s_nop 0
	v_cvt_pk_bf16_f32 v5, v12, v13
	global_store_dwordx4 v[0:1], v[2:5], off sc1
	v_add_u32_e32 v1, 0x800, v230
	v_mul_hi_i32 v0, v1, s74
	v_lshrrev_b32_e32 v2, 31, v0
	v_ashrrev_i32_e32 v0, 3, v0
	v_add_u32_e32 v0, v0, v2
	v_mul_lo_u32 v2, v0, 48
	v_sub_u32_e32 v12, v1, v2
	v_ashrrev_i32_e32 v1, 31, v0
	v_lshl_add_u64 v[20:21], s[12:13], 0, v[0:1]
	v_mad_u64_u32 v[4:5], s[6:7], v20, s70, v[8:9]
	v_mov_b32_e32 v6, v5
	v_lshlrev_b32_e32 v2, 3, v12
	v_mad_u64_u32 v[6:7], s[6:7], v21, s70, v[6:7]
	v_mov_b32_e32 v5, v6
	v_ashrrev_i32_e32 v3, 31, v2
	v_lshl_add_u64 v[4:5], v[4:5], 0, s[56:57]
	v_lshlrev_b64 v[22:23], 1, v[2:3]
	v_lshl_add_u64 v[4:5], v[4:5], 0, v[22:23]
	v_add_co_u32_e32 v4, vcc, s80, v4
	v_lshl_add_u32 v13, v0, 2, 0
	s_nop 0
	v_addc_co_u32_e32 v5, vcc, 0, v5, vcc
	global_load_dwordx4 v[4:7], v[4:5], off offset:3072 sc1
	v_mul_lo_u32 v14, v0, s79
	v_lshlrev_b32_e32 v12, 4, v12
	v_add3_u32 v12, v13, v14, v12
	ds_read2st64_b32 v[24:25], v13 offset0:16 offset1:17
	ds_read2st64_b32 v[26:27], v13 offset0:18 offset1:19
	ds_read_b128 v[12:15], v12 offset:63488
	v_lshl_add_u64 v[16:17], v[2:3], 2, s[18:19]
	s_waitcnt lgkmcnt(0)
	v_lshlrev_b32_e32 v30, 16, v12
	v_and_b32_e32 v31, 0xffff0000, v12
	s_waitcnt vmcnt(0)
	v_lshlrev_b32_e32 v32, 16, v4
	v_and_b32_e32 v4, 0xffff0000, v4
	v_mul_f32_e32 v0, 0xbfb8aa3b, v32
	v_mul_f32_e32 v1, 0xbfb8aa3b, v4
	v_exp_f32_e32 v0, v0
	v_exp_f32_e32 v1, v1
	v_lshlrev_b32_e32 v37, 16, v5
	v_lshlrev_b32_e32 v40, 16, v6
	v_and_b32_e32 v6, 0xffff0000, v6
	v_pk_add_f32 v[28:29], v[0:1], 1.0 op_sel_hi:[1,0]
	global_load_dwordx4 v[0:3], v[16:17], off offset:16
	s_nop 0
	global_load_dwordx4 v[16:19], v[16:17], off
	v_lshlrev_b32_e32 v41, 16, v7
	v_and_b32_e32 v7, 0xffff0000, v7
	v_rcp_f32_e32 v12, v29
	s_nop 0
	v_mul_f32_e32 v29, v4, v12
	v_and_b32_e32 v35, 0xffff0000, v5
	v_mul_f32_e32 v4, 0xbfb8aa3b, v37
	v_mul_f32_e32 v5, 0xbfb8aa3b, v35
	v_exp_f32_e32 v4, v4
	v_exp_f32_e32 v5, v5
	v_rcp_f32_e32 v12, v28
	s_nop 0
	v_mul_f32_e32 v28, v32, v12
	v_pk_add_f32 v[4:5], v[4:5], 1.0 op_sel_hi:[1,0]
	v_lshlrev_b32_e32 v12, 16, v13
	v_and_b32_e32 v13, 0xffff0000, v13
	v_rcp_f32_e32 v32, v5
	s_nop 0
	v_mul_f32_e32 v33, v35, v32
	v_mul_f32_e32 v34, 0xbfb8aa3b, v40
	v_mul_f32_e32 v35, 0xbfb8aa3b, v6
	v_exp_f32_e32 v34, v34
	v_exp_f32_e32 v35, v35
	v_rcp_f32_e32 v5, v4
	s_nop 0
	v_mul_f32_e32 v32, v37, v5
	v_pk_add_f32 v[34:35], v[34:35], 1.0 op_sel_hi:[1,0]
	v_lshlrev_b32_e32 v36, 16, v14
	v_and_b32_e32 v37, 0xffff0000, v14
	v_rcp_f32_e32 v4, v35
	s_nop 0
	v_mul_f32_e32 v35, v6, v4
	v_mul_f32_e32 v4, 0xbfb8aa3b, v41
	v_mul_f32_e32 v5, 0xbfb8aa3b, v7
	v_exp_f32_e32 v4, v4
	v_exp_f32_e32 v5, v5
	v_rcp_f32_e32 v6, v34
	s_nop 0
	v_mul_f32_e32 v34, v40, v6
	v_pk_add_f32 v[4:5], v[4:5], 1.0 op_sel_hi:[1,0]
	v_lshlrev_b32_e32 v14, 16, v15
	v_and_b32_e32 v15, 0xffff0000, v15
	v_rcp_f32_e32 v6, v5
	s_nop 0
	v_mul_f32_e32 v39, v7, v6
	v_div_scale_f32 v5, vcc, v41, v4, v41
	v_rcp_f32_e32 v5, v4
	s_nop 0
	v_mul_f32_e32 v38, v41, v5
	v_lshlrev_b64 v[4:5], 12, v[20:21]
	v_add_u32_e32 v21, 0xa00, v230
	v_mul_hi_i32 v6, v21, s74
	v_lshrrev_b32_e32 v7, 31, v6
	v_ashrrev_i32_e32 v6, 3, v6
	v_add_u32_e32 v20, v6, v7
	v_lshl_add_u32 v42, v20, 2, 0
	ds_read2st64_b32 v[6:7], v42 offset0:16 offset1:17
	v_lshl_add_u64 v[4:5], s[16:17], 0, v[4:5]
	v_lshl_add_u64 v[22:23], v[4:5], 0, v[22:23]
	ds_read2st64_b32 v[4:5], v42 offset0:18 offset1:19
	v_mov_b32_e32 v41, v24
	s_waitcnt lgkmcnt(1)
	v_mov_b32_e32 v40, v6
	v_mov_b32_e32 v24, v7
	v_pk_add_f32 v[6:7], v[40:41], v[24:25]
	s_waitcnt lgkmcnt(0)
	v_mov_b32_e32 v24, v4
	v_mov_b32_e32 v25, v26
	v_pk_add_f32 v[6:7], v[6:7], v[24:25]
	v_mov_b32_e32 v26, v5
	v_pk_add_f32 v[4:5], v[6:7], v[26:27]
	v_mul_lo_u32 v43, v20, 48
	v_pk_fma_f32 v[24:25], v[4:5], s[64:65], v[10:11] op_sel_hi:[1,0,0]
	s_nop 0
	v_mul_f32_e32 v4, 0x4b800000, v25
	v_cmp_gt_f32_e32 vcc, s81, v25
	s_nop 1
	v_cndmask_b32_e32 v4, v25, v4, vcc
	v_rsq_f32_e32 v4, v4
	v_sub_u32_e32 v25, v21, v43
	v_ashrrev_i32_e32 v21, 31, v20
	v_lshlrev_b32_e32 v10, 3, v25
	v_mul_f32_e32 v5, 0x45800000, v4
	v_cndmask_b32_e32 v26, v4, v5, vcc
	v_pk_mul_f32 v[4:5], v[26:27], v[30:31] op_sel_hi:[0,1]
	v_pk_mul_f32 v[6:7], v[26:27], v[12:13] op_sel_hi:[0,1]
	s_waitcnt vmcnt(0)
	v_pk_mul_f32 v[4:5], v[16:17], v[4:5]
	v_pk_mul_f32 v[6:7], v[18:19], v[6:7]
	v_pk_mul_f32 v[4:5], v[28:29], v[4:5]
	v_pk_mul_f32 v[6:7], v[32:33], v[6:7]
	v_cvt_pk_bf16_f32 v4, v4, v5
	v_cvt_pk_bf16_f32 v5, v6, v7
	v_pk_mul_f32 v[6:7], v[26:27], v[36:37] op_sel_hi:[0,1]
	v_pk_mul_f32 v[0:1], v[0:1], v[6:7]
	v_ashrrev_i32_e32 v11, 31, v10
	v_pk_mul_f32 v[0:1], v[34:35], v[0:1]
	v_lshlrev_b64 v[18:19], 1, v[10:11]
	v_cvt_pk_bf16_f32 v6, v0, v1
	v_pk_mul_f32 v[0:1], v[26:27], v[14:15] op_sel_hi:[0,1]
	v_pk_mul_f32 v[0:1], v[2:3], v[0:1]
	v_lshl_add_u64 v[10:11], v[10:11], 2, s[18:19]
	v_pk_mul_f32 v[0:1], v[38:39], v[0:1]
	v_mul_f32_e32 v14, 0x4b800000, v24
	v_cvt_pk_bf16_f32 v7, v0, v1
	v_lshl_add_u64 v[0:1], s[12:13], 0, v[20:21]
	v_mad_u64_u32 v[2:3], s[6:7], v0, s70, v[8:9]
	global_store_dwordx4 v[22:23], v[4:7], off sc1
	v_lshlrev_b32_e32 v15, 4, v25
	s_nop 0
	v_mov_b32_e32 v4, v3
	v_mad_u64_u32 v[4:5], s[6:7], v1, s70, v[4:5]
	v_mov_b32_e32 v3, v4
	v_lshl_add_u64 v[2:3], v[2:3], 0, s[56:57]
	v_lshl_add_u64 v[2:3], v[2:3], 0, v[18:19]
	v_add_co_u32_e32 v2, vcc, s80, v2
	v_lshlrev_b64 v[0:1], 12, v[0:1]
	s_nop 0
	v_addc_co_u32_e32 v3, vcc, 0, v3, vcc
	global_load_dwordx4 v[2:5], v[2:3], off offset:3072 sc1
	s_nop 0
	global_load_dwordx4 v[6:9], v[10:11], off
	s_nop 0
	global_load_dwordx4 v[10:13], v[10:11], off offset:16
	v_cmp_gt_f32_e32 vcc, s81, v24
	v_lshl_add_u64 v[0:1], s[16:17], 0, v[0:1]
	v_lshl_add_u64 v[0:1], v[0:1], 0, v[18:19]
	v_cndmask_b32_e32 v14, v24, v14, vcc
	v_rsq_f32_e32 v22, v14
	v_mul_lo_u32 v14, v20, s79
	v_add3_u32 v14, v42, v14, v15
	ds_read_b128 v[14:17], v14 offset:63488
	v_mul_f32_e32 v24, 0x45800000, v22
	v_cndmask_b32_e32 v22, v22, v24, vcc
	s_waitcnt lgkmcnt(0)
	v_lshlrev_b32_e32 v24, 16, v14
	v_and_b32_e32 v25, 0xffff0000, v14
	s_waitcnt vmcnt(2)
	v_lshlrev_b32_e32 v23, 16, v2
	v_and_b32_e32 v2, 0xffff0000, v2
	v_mul_f32_e32 v20, 0xbfb8aa3b, v23
	v_mul_f32_e32 v21, 0xbfb8aa3b, v2
	v_exp_f32_e32 v20, v20
	v_exp_f32_e32 v21, v21
	v_pk_mul_f32 v[24:25], v[22:23], v[24:25] op_sel_hi:[0,1]
	s_waitcnt vmcnt(1)
	v_pk_mul_f32 v[6:7], v[6:7], v[24:25]
	v_pk_add_f32 v[20:21], v[20:21], 1.0 op_sel_hi:[1,0]
	s_nop 0
	v_div_scale_f32 v26, s[6:7], v21, v21, v2
	v_rcp_f32_e32 v27, v26
	s_nop 0
	v_fma_f32 v14, -v26, v27, 1.0
	v_fmac_f32_e32 v27, v14, v27
	v_div_scale_f32 v25, s[6:7], v20, v20, v23
	v_rcp_f32_e32 v26, v25
	v_rcp_f32_e32 v14, v21
	s_nop 0
	v_mul_f32_e32 v21, v2, v14
	v_fma_f32 v2, -v25, v26, 1.0
	v_fmac_f32_e32 v26, v2, v26
	v_lshlrev_b32_e32 v14, 16, v3
	v_rcp_f32_e32 v2, v20
	s_nop 0
	v_mul_f32_e32 v20, v23, v2
	v_and_b32_e32 v23, 0xffff0000, v3
	v_mul_f32_e32 v2, 0xbfb8aa3b, v14
	v_exp_f32_e32 v24, v2
	v_mul_f32_e32 v2, 0xbfb8aa3b, v23
	v_exp_f32_e32 v25, v2
	v_pk_mul_f32 v[2:3], v[20:21], v[6:7]
	v_lshlrev_b32_e32 v6, 16, v15
	v_cvt_pk_bf16_f32 v2, v2, v3
	v_pk_add_f32 v[20:21], v[24:25], 1.0 op_sel_hi:[1,0]
	v_and_b32_e32 v7, 0xffff0000, v15
	v_div_scale_f32 v3, s[6:7], v21, v21, v23
	v_rcp_f32_e32 v24, v3
	v_pk_mul_f32 v[6:7], v[22:23], v[6:7] op_sel_hi:[0,1]
	v_pk_mul_f32 v[6:7], v[8:9], v[6:7]
	v_fma_f32 v8, -v3, v24, 1.0
	v_fmac_f32_e32 v24, v8, v24
	v_div_scale_f32 v8, s[6:7], v20, v20, v14
	v_rcp_f32_e32 v15, v8
	v_rcp_f32_e32 v3, v21
	s_nop 0
	v_mul_f32_e32 v9, v23, v3
	v_fma_f32 v3, -v8, v15, 1.0
	v_fmac_f32_e32 v15, v3, v15
	v_div_scale_f32 v3, vcc, v14, v20, v14
	v_mul_f32_e32 v21, v3, v15
	v_fma_f32 v23, -v8, v21, v3
	v_fmac_f32_e32 v21, v23, v15
	v_rcp_f32_e32 v3, v20
	s_nop 0
	v_mul_f32_e32 v8, v14, v3
	v_lshlrev_b32_e32 v20, 16, v4
	v_and_b32_e32 v4, 0xffff0000, v4
	v_mul_f32_e32 v3, 0xbfb8aa3b, v20
	v_exp_f32_e32 v14, v3
	v_mul_f32_e32 v3, 0xbfb8aa3b, v4
	v_exp_f32_e32 v15, v3
	v_pk_mul_f32 v[6:7], v[8:9], v[6:7]
	v_pk_add_f32 v[8:9], v[14:15], 1.0 op_sel_hi:[1,0]
	s_nop 0
	v_cvt_pk_bf16_f32 v3, v6, v7
	v_lshlrev_b32_e32 v6, 16, v16
	v_and_b32_e32 v7, 0xffff0000, v16
	v_pk_mul_f32 v[6:7], v[22:23], v[6:7] op_sel_hi:[0,1]
	s_waitcnt vmcnt(0)
	v_pk_mul_f32 v[6:7], v[10:11], v[6:7]
	v_div_scale_f32 v14, s[6:7], v8, v8, v20
	v_rcp_f32_e32 v16, v14
	v_rcp_f32_e32 v10, v9
	s_nop 0
	v_mul_f32_e32 v9, v4, v10
	v_and_b32_e32 v15, 0xffff0000, v5
	v_fma_f32 v4, -v14, v16, 1.0
	v_fmac_f32_e32 v16, v4, v16
	v_lshlrev_b32_e32 v14, 16, v5
	v_rcp_f32_e32 v4, v8
	s_nop 0
	v_mul_f32_e32 v8, v20, v4
	v_mul_f32_e32 v4, 0xbfb8aa3b, v14
	v_exp_f32_e32 v10, v4
	v_mul_f32_e32 v4, 0xbfb8aa3b, v15
	v_exp_f32_e32 v11, v4
	v_pk_mul_f32 v[4:5], v[8:9], v[6:7]
	v_lshlrev_b32_e32 v6, 16, v17
	v_cvt_pk_bf16_f32 v4, v4, v5
	v_pk_add_f32 v[8:9], v[10:11], 1.0 op_sel_hi:[1,0]
	v_and_b32_e32 v7, 0xffff0000, v17
	v_pk_mul_f32 v[6:7], v[22:23], v[6:7] op_sel_hi:[0,1]
	v_pk_mul_f32 v[6:7], v[12:13], v[6:7]
	v_div_scale_f32 v11, s[6:7], v8, v8, v14
	v_rcp_f32_e32 v13, v11
	v_rcp_f32_e32 v5, v9
	s_nop 0
	v_mul_f32_e32 v9, v15, v5
	v_fma_f32 v5, -v11, v13, 1.0
	v_fmac_f32_e32 v13, v5, v13
	v_div_scale_f32 v5, vcc, v14, v8, v14
	v_mul_f32_e32 v10, v5, v13
	v_fma_f32 v12, -v11, v10, v5
	v_fmac_f32_e32 v10, v12, v13
	v_rcp_f32_e32 v5, v8
	s_nop 0
	v_mul_f32_e32 v8, v14, v5
	v_pk_mul_f32 v[6:7], v[8:9], v[6:7]
	s_andn2_b64 vcc, exec, s[14:15]
	v_cvt_pk_bf16_f32 v5, v6, v7
	global_store_dwordx4 v[0:1], v[2:5], off sc1
	s_barrier
	s_cbranch_vccz .LBB0_628

.LBB0_612:
	s_ashr_i32 s8, s82, 8
	s_ashr_i32 s9, s8, 31
	s_and_b32 s10, s3, 0xfc0
	s_mul_i32 s12, s82, 0x24000
	s_mul_hi_i32 s11, s82, 0x24000
	s_add_u32 s14, s65, s12
	v_and_b32_e32 v241, 63, v230
	v_cvt_pk_bf16_f32 v168, v0, v1
	v_cvt_pk_bf16_f32 v169, v2, v3
	v_cvt_pk_bf16_f32 v170, v4, v5
	v_cvt_pk_bf16_f32 v171, v6, v7
	v_cvt_pk_bf16_f32 v164, v8, v9
	v_cvt_pk_bf16_f32 v165, v10, v11
	v_cvt_pk_bf16_f32 v166, v12, v13
	v_cvt_pk_bf16_f32 v167, v14, v15
	s_addc_u32 s15, s67, s11
	s_lshl_b64 s[12:13], s[8:9], 12
	s_and_b32 s16, s82, 3
	v_cvt_pk_bf16_f32 v172, v172, v17
	v_cvt_pk_bf16_f32 v173, v18, v19
	v_cvt_pk_bf16_f32 v174, v20, v21
	v_cvt_pk_bf16_f32 v175, v22, v23
	s_ashr_i32 s17, s56, 7
	s_mul_i32 s18, s17, 0x900
	s_add_i32 s8, s18, 0x300
	v_or_b32_e32 v0, s8, v241
	v_ashrrev_i32_e32 v1, 31, v0
	v_lshl_add_u64 v[16:17], v[0:1], 4, s[14:15]
	v_mfma_f32_32x32x16_bf16 v[0:15], v[48:51], v[32:35], 0
	s_add_i32 s8, s18, 0x340
	v_or_b32_e32 v18, s8, v241
	s_add_i32 s8, s18, 0x380
	v_ashrrev_i32_e32 v19, 31, v18
	v_or_b32_e32 v20, s8, v241
	v_lshl_add_u64 v[18:19], v[18:19], 4, s[14:15]
	v_ashrrev_i32_e32 v21, 31, v20
	v_mfma_f32_32x32x16_bf16 v[0:15], v[52:55], v[120:123], v[0:15]
	s_add_i32 s8, s18, 0x3c0
	v_lshl_add_u64 v[20:21], v[20:21], 4, s[14:15]
	global_load_dwordx4 v[40:43], v[18:19], off sc1
	global_load_dwordx4 v[36:39], v[20:21], off sc1
	v_or_b32_e32 v18, s8, v241
	s_add_i32 s8, s18, 0x400
	v_ashrrev_i32_e32 v19, 31, v18
	v_or_b32_e32 v20, s8, v241
	v_mfma_f32_32x32x16_bf16 v[0:15], v[56:59], v[128:131], v[0:15]
	v_lshl_add_u64 v[18:19], v[18:19], 4, s[14:15]
	v_ashrrev_i32_e32 v21, 31, v20
	s_add_i32 s8, s18, 0x440
	v_lshl_add_u64 v[20:21], v[20:21], 4, s[14:15]
	global_load_dwordx4 v[176:179], v[18:19], off sc1
	global_load_dwordx4 v[44:47], v[20:21], off sc1
	v_or_b32_e32 v18, s8, v241
	s_add_i32 s8, s18, 0x480
	v_mfma_f32_32x32x16_bf16 v[0:15], v[60:63], v[124:127], v[0:15]
	v_ashrrev_i32_e32 v19, 31, v18
	v_or_b32_e32 v20, s8, v241
	v_lshl_add_u64 v[18:19], v[18:19], 4, s[14:15]
	v_ashrrev_i32_e32 v21, 31, v20
	s_add_i32 s8, s18, 0x4c0
	v_lshl_add_u64 v[20:21], v[20:21], 4, s[14:15]
	global_load_dwordx4 v[184:187], v[18:19], off sc1
	global_load_dwordx4 v[180:183], v[20:21], off sc1
	v_mfma_f32_32x32x16_bf16 v[0:15], v[64:67], v[136:139], v[0:15]
	v_or_b32_e32 v18, s8, v241
	s_add_i32 s8, s18, 0x500
	v_or_b32_e32 v20, s8, v241
	s_mul_i32 s8, s17, 3
	s_mul_i32 s9, s16, 12
	s_add_i32 s8, s8, s9
	v_lshlrev_b32_e32 v216, 4, v241
	v_mfma_f32_32x32x16_bf16 v[0:15], v[68:71], v[132:135], v[0:15]
	s_ashr_i32 s9, s8, 31
	s_or_b32 s12, s12, s10
	v_lshl_add_u64 v[224:225], s[58:59], 0, v[216:217]
	s_lshl_b64 s[20:21], s[8:9], 20
	v_ashrrev_i32_e32 v19, 31, v18
	s_lshl_b64 s[10:11], s[12:13], 6
	v_lshl_add_u64 v[22:23], v[224:225], 0, s[20:21]
	v_mfma_f32_32x32x16_bf16 v[0:15], v[72:75], v[144:147], v[0:15]
	v_lshl_add_u64 v[18:19], v[18:19], 4, s[14:15]
	v_ashrrev_i32_e32 v21, 31, v20
	v_lshl_add_u64 v[24:25], v[22:23], 0, s[10:11]
	s_add_i32 s19, s18, 0x540
	v_lshl_add_u64 v[20:21], v[20:21], 4, s[14:15]
	global_load_dwordx4 v[244:247], v[24:25], off
	global_load_dwordx4 v[200:203], v[18:19], off sc1
	global_load_dwordx4 v[192:195], v[20:21], off sc1
	v_mfma_f32_32x32x16_bf16 v[0:15], v[76:79], v[140:143], v[0:15]
	v_or_b32_e32 v18, s19, v241
	s_add_i32 s19, s18, 0x580
	v_ashrrev_i32_e32 v19, 31, v18
	v_or_b32_e32 v20, s19, v241
	v_lshl_add_u64 v[18:19], v[18:19], 4, s[14:15]
	v_ashrrev_i32_e32 v21, 31, v20
	s_add_i32 s19, s18, 0x5c0
	v_lshl_add_u64 v[20:21], v[20:21], 4, s[14:15]
	global_load_dwordx4 v[204:207], v[18:19], off sc1
	global_load_dwordx4 v[196:199], v[20:21], off sc1
	v_or_b32_e32 v18, s19, v241
	s_add_i32 s19, s18, 0x600
	v_or_b32_e32 v48, s19, v241
	v_ashrrev_i32_e32 v19, 31, v18
	v_ashrrev_i32_e32 v49, 31, v48
	v_mfma_f32_32x32x16_bf16 v[0:15], v[84:87], v[152:155], v[0:15]
	v_lshl_add_u64 v[30:31], v[18:19], 4, s[14:15]
	v_lshl_add_u64 v[48:49], v[48:49], 4, s[14:15]
	s_add_i32 s19, s18, 0x640
	global_load_dwordx4 v[248:251], v[24:25], off offset:1024
	s_nop 0
	global_load_dwordx4 v[16:19], v[16:17], off sc1
	s_nop 0
	global_load_dwordx4 v[20:23], v[24:25], off offset:3072
	global_load_dwordx4 v[208:211], v[30:31], off sc1
	s_nop 0
	global_load_dwordx4 v[48:51], v[48:49], off sc1
	v_or_b32_e32 v30, s19, v241
	s_add_i32 s19, s18, 0x680
	v_or_b32_e32 v52, s19, v241
	v_ashrrev_i32_e32 v31, 31, v30
	v_ashrrev_i32_e32 v53, 31, v52
	v_lshl_add_u64 v[30:31], v[30:31], 4, s[14:15]
	v_lshl_add_u64 v[56:57], v[52:53], 4, s[14:15]
	s_add_i32 s19, s18, 0x6c0
	global_load_dwordx4 v[52:55], v[30:31], off sc1
	s_nop 0
	global_load_dwordx4 v[56:59], v[56:57], off sc1
	v_or_b32_e32 v30, s19, v241
	s_add_i32 s19, s18, 0x700
	v_or_b32_e32 v60, s19, v241
	v_ashrrev_i32_e32 v31, 31, v30
	v_ashrrev_i32_e32 v61, 31, v60
	v_mfma_f32_32x32x16_bf16 v[0:15], v[92:95], v[148:151], v[0:15]
	v_lshl_add_u64 v[30:31], v[30:31], 4, s[14:15]
	v_lshl_add_u64 v[64:65], v[60:61], 4, s[14:15]
	s_add_i32 s19, s18, 0x740
	global_load_dwordx4 v[60:63], v[30:31], off sc1
	s_nop 0
	global_load_dwordx4 v[64:67], v[64:65], off sc1
	v_or_b32_e32 v30, s19, v241
	s_add_i32 s19, s18, 0x780
	v_or_b32_e32 v68, s19, v241
	v_ashrrev_i32_e32 v31, 31, v30
	v_ashrrev_i32_e32 v69, 31, v68
	v_lshl_add_u64 v[30:31], v[30:31], 4, s[14:15]
	v_lshl_add_u64 v[72:73], v[68:69], 4, s[14:15]
	s_add_i32 s19, s18, 0x7c0
	global_load_dwordx4 v[68:71], v[30:31], off sc1
	s_nop 0
	global_load_dwordx4 v[72:75], v[72:73], off sc1
	v_or_b32_e32 v30, s19, v241
	s_add_i32 s19, s18, 0x800
	v_or_b32_e32 v76, s19, v241
	v_ashrrev_i32_e32 v31, 31, v30
	v_ashrrev_i32_e32 v77, 31, v76
	v_mfma_f32_32x32x16_bf16 v[0:15], v[96:99], v[156:159], v[0:15]
	v_lshl_add_u64 v[30:31], v[30:31], 4, s[14:15]
	v_lshl_add_u64 v[84:85], v[76:77], 4, s[14:15]
	s_add_i32 s19, s18, 0x840
	global_load_dwordx4 v[76:79], v[30:31], off sc1
	s_nop 0
	global_load_dwordx4 v[84:87], v[84:85], off sc1
	v_or_b32_e32 v30, s19, v241
	s_add_i32 s19, s18, 0x880
	v_or_b32_e32 v92, s19, v241
	v_ashrrev_i32_e32 v31, 31, v30
	v_ashrrev_i32_e32 v93, 31, v92
	v_lshl_add_u64 v[30:31], v[30:31], 4, s[14:15]
	v_lshl_add_u64 v[96:97], v[92:93], 4, s[14:15]
	s_addk_i32 s18, 0x8c0
	global_load_dwordx4 v[92:95], v[30:31], off sc1
	s_nop 0
	global_load_dwordx4 v[96:99], v[96:97], off sc1
	v_or_b32_e32 v30, s18, v241
	v_ashrrev_i32_e32 v31, 31, v30
	v_lshl_add_u64 v[30:31], v[30:31], 4, s[14:15]
	v_mfma_f32_32x32x16_bf16 v[0:15], v[100:103], v[160:163], v[0:15]
	global_load_dwordx4 v[100:103], v[30:31], off sc1
	s_and_b64 vcc, exec, s[6:7]
	s_waitcnt vmcnt(20)
	v_mfma_f32_32x32x16_bf16 v[0:15], v[244:247], v[168:171], v[0:15]
	s_waitcnt vmcnt(15)
	v_mfma_f32_32x32x16_bf16 v[0:15], v[248:251], v[164:167], v[0:15]
	s_cbranch_vccnz .LBB0_614
	global_load_dwordx4 v[244:247], v[24:25], off offset:2048
	s_waitcnt vmcnt(0)
	v_mfma_f32_32x32x16_bf16 v[0:15], v[244:247], v[172:175], v[0:15]

.LBB0_624:
	s_add_i32 s82, s82, s46
	s_cmpk_gt_i32 s82, 0x3ff
	s_waitcnt vmcnt(0)
	s_nop 8
	v_cvt_pk_bf16_f32 v120, v32, v33
	v_cvt_pk_bf16_f32 v121, v34, v35
	v_cvt_pk_bf16_f32 v122, v36, v37
	v_cvt_pk_bf16_f32 v123, v38, v39
	s_cselect_b64 s[14:15], -1, 0
	ds_write2_b64 v176, v[120:121], v[122:123] offset0:16 offset1:18
	v_cvt_pk_bf16_f32 v120, v40, v41
	v_cvt_pk_bf16_f32 v121, v42, v43
	v_cvt_pk_bf16_f32 v122, v44, v45
	v_cvt_pk_bf16_f32 v123, v46, v47
	s_and_b64 vcc, exec, s[14:15]
	ds_write2_b64 v176, v[120:121], v[122:123] offset0:20 offset1:22
	s_cbranch_vccnz .LBB0_626
	s_ashr_i32 s6, s82, 8
	s_ashr_i32 s7, s6, 31
	s_add_i32 s8, s73, s3
	s_lshl_b64 s[6:7], s[6:7], 12
	s_and_b32 s8, s8, 0xfc0
	s_or_b32 s6, s6, s8
	s_mul_i32 s8, s82, 0x24000
	s_mul_hi_i32 s9, s82, 0x24000
	s_add_u32 s8, s65, s8
	v_readfirstlane_b32 s10, v230
	s_addc_u32 s9, s67, s9
	s_lshr_b32 s10, s10, 7
	s_mulk_i32 s10, 0x900
	s_add_i32 s11, s10, 0x100
	v_or_b32_e32 v64, s11, v241
	s_add_i32 s11, s10, 0x140
	v_or_b32_e32 v66, s11, v241
	s_add_i32 s11, s10, 0x180
	v_or_b32_e32 v56, s10, v241
	v_or_b32_e32 v72, s11, v241
	s_add_i32 s11, s10, 0x1c0
	v_ashrrev_i32_e32 v57, 31, v56
	v_or_b32_e32 v74, s11, v241
	s_add_i32 s11, s10, 0x200
	v_lshl_add_u64 v[48:49], v[56:57], 4, s[8:9]
	v_or_b32_e32 v50, 64, v56
	v_or_b32_e32 v58, 0x80, v56
	v_or_b32_e32 v56, 0xc0, v56
	v_or_b32_e32 v80, s11, v241
	s_add_i32 s11, s10, 0x240
	v_ashrrev_i32_e32 v51, 31, v50
	v_ashrrev_i32_e32 v59, 31, v58
	v_ashrrev_i32_e32 v57, 31, v56
	v_ashrrev_i32_e32 v65, 31, v64
	v_ashrrev_i32_e32 v67, 31, v66
	v_ashrrev_i32_e32 v73, 31, v72
	v_ashrrev_i32_e32 v75, 31, v74
	v_ashrrev_i32_e32 v81, 31, v80
	v_or_b32_e32 v82, s11, v241
	v_lshl_add_u64 v[52:53], v[50:51], 4, s[8:9]
	v_lshl_add_u64 v[58:59], v[58:59], 4, s[8:9]
	v_lshl_add_u64 v[60:61], v[56:57], 4, s[8:9]
	v_lshl_add_u64 v[64:65], v[64:65], 4, s[8:9]
	v_lshl_add_u64 v[68:69], v[66:67], 4, s[8:9]
	v_lshl_add_u64 v[72:73], v[72:73], 4, s[8:9]
	v_lshl_add_u64 v[76:77], v[74:75], 4, s[8:9]
	v_lshl_add_u64 v[80:81], v[80:81], 4, s[8:9]
	v_ashrrev_i32_e32 v83, 31, v82
	s_add_i32 s11, s10, 0x280
	global_load_dwordx4 v[48:51], v[48:49], off sc1
	s_nop 0
	global_load_dwordx4 v[52:55], v[52:53], off sc1
	s_nop 0
	global_load_dwordx4 v[56:59], v[58:59], off sc1
	s_nop 0
	global_load_dwordx4 v[60:63], v[60:61], off sc1
	s_nop 0
	global_load_dwordx4 v[64:67], v[64:65], off sc1
	s_nop 0
	global_load_dwordx4 v[68:71], v[68:69], off sc1
	s_nop 0
	global_load_dwordx4 v[72:75], v[72:73], off sc1
	s_nop 0
	global_load_dwordx4 v[76:79], v[76:77], off sc1
	v_lshl_add_u64 v[82:83], v[82:83], 4, s[8:9]
	global_load_dwordx4 v[84:87], v[80:81], off sc1
	global_load_dwordx4 v[92:95], v[82:83], off sc1
	v_or_b32_e32 v80, s11, v241
	s_addk_i32 s10, 0x2c0
	v_ashrrev_i32_e32 v81, 31, v80
	v_or_b32_e32 v82, s10, v241
	v_lshl_add_u64 v[80:81], v[80:81], 4, s[8:9]
	v_ashrrev_i32_e32 v83, 31, v82
	v_ashrrev_i32_e32 v223, 31, v222
	v_lshl_add_u64 v[82:83], v[82:83], 4, s[8:9]
	global_load_dwordx4 v[96:99], v[80:81], off sc1
	global_load_dwordx4 v[100:103], v[82:83], off sc1
	v_lshl_add_u64 v[80:81], s[6:7], 0, v[222:223]
	v_mov_b64_e32 v[112:113], s[54:55]
	s_and_b32 s10, s82, 3
	v_mad_u64_u32 v[82:83], s[8:9], v80, s70, v[112:113]
	v_mad_i32_i24 v83, v81, s70, v83
	s_mul_i32 s56, s10, 0x180
	v_lshl_add_u64 v[80:81], v[82:83], 0, s[56:57]
	v_lshlrev_b32_e32 v82, 3, v221
	v_ashrrev_i32_e32 v221, 31, v220
	v_lshl_add_u64 v[104:105], s[6:7], 0, v[220:221]
	v_mad_u64_u32 v[106:107], s[8:9], v104, s70, v[112:113]
	v_mad_i32_i24 v107, v105, s70, v107
	v_lshl_add_u64 v[104:105], v[106:107], 0, s[56:57]
	v_lshlrev_b32_e32 v106, 3, v219
	v_ashrrev_i32_e32 v219, 31, v218
	v_lshl_add_u64 v[114:115], s[6:7], 0, v[218:219]
	v_mad_u64_u32 v[112:113], s[6:7], v114, s70, v[112:113]
	v_mad_i32_i24 v113, v115, s70, v113
	v_lshlrev_b32_e32 v114, 3, v240
	v_ashrrev_i32_e32 v83, 31, v82
	v_ashrrev_i32_e32 v107, 31, v106
	v_lshl_add_u64 v[112:113], v[112:113], 0, s[56:57]
	v_ashrrev_i32_e32 v115, 31, v114
	v_lshl_add_u64 v[88:89], v[82:83], 1, v[80:81]
	v_lshl_add_u64 v[108:109], v[106:107], 1, v[104:105]
	v_lshl_add_u64 v[116:117], v[114:115], 1, v[112:113]
	global_load_dwordx4 v[80:83], v[88:89], off offset:1536
	s_nop 0
	global_load_dwordx4 v[88:91], v[88:89], off
	s_nop 0
	global_load_dwordx4 v[104:107], v[108:109], off offset:1536
	s_nop 0
	global_load_dwordx4 v[108:111], v[108:109], off
	s_nop 0
	global_load_dwordx4 v[112:115], v[116:117], off offset:1536
	s_nop 0
	global_load_dwordx4 v[116:119], v[116:117], off

.LBB0_756:
	v_ashrrev_i32_e32 v73, 31, v72
	v_lshlrev_b64 v[86:87], 12, v[72:73]
	v_lshl_add_u64 v[32:33], v[74:75], 0, v[86:87]
	global_load_dwordx2 v[56:57], v[32:33], off sc1
	global_load_dwordx2 v[58:59], v[32:33], off offset:512 sc1
	global_load_dwordx2 v[60:61], v[32:33], off offset:1024 sc1
	global_load_dwordx2 v[62:63], v[32:33], off offset:1536 sc1
	global_load_dwordx2 v[64:65], v[32:33], off offset:2560 sc1
	global_load_dwordx2 v[66:67], v[32:33], off offset:2048 sc1
	global_load_dwordx2 v[68:69], v[32:33], off offset:3584 sc1
	global_load_dwordx2 v[84:85], v[32:33], off offset:3072 sc1
	v_lshlrev_b64 v[88:89], 13, v[72:73]
	v_lshl_add_u64 v[32:33], v[80:81], 0, v[88:89]
	v_add_co_u32_e32 v94, vcc, s3, v32
	global_load_dwordx4 v[52:55], v[32:33], off nt
	global_load_dwordx4 v[48:51], v[32:33], off offset:1024 nt
	global_load_dwordx4 v[44:47], v[32:33], off offset:2048 nt
	global_load_dwordx4 v[40:43], v[32:33], off offset:3072 nt
	v_addc_co_u32_e32 v95, vcc, 0, v33, vcc
	global_load_dwordx4 v[36:39], v[94:95], off nt
	global_load_dwordx4 v[32:35], v[94:95], off offset:1024 nt
	global_load_dwordx4 v[90:93], v[94:95], off offset:2048 nt
	v_lshl_add_u64 v[88:89], v[76:77], 0, v[88:89]
	global_load_dwordx4 v[94:97], v[94:95], off offset:3072 nt
	v_lshl_add_u64 v[86:87], v[78:79], 0, v[86:87]
	s_waitcnt vmcnt(0)
	v_and_b32_e32 v99, 0xffff0000, v56
	v_and_b32_e32 v101, 0xffff0000, v58
	v_lshlrev_b32_e32 v98, 16, v56
	v_lshlrev_b32_e32 v100, 16, v58
	v_and_b32_e32 v103, 0xffff0000, v60
	v_lshlrev_b32_e32 v56, 16, v57
	v_lshlrev_b32_e32 v71, 16, v68
	v_and_b32_e32 v115, 0xffff0000, v68
	v_lshlrev_b32_e32 v117, 16, v69
	v_and_b32_e32 v119, 0xffff0000, v69
	v_mul_f32_e32 v68, v99, v99
	v_mul_f32_e32 v69, v101, v101
	v_lshlrev_b32_e32 v58, 16, v59
	v_lshlrev_b32_e32 v102, 16, v60
	v_and_b32_e32 v105, 0xffff0000, v62
	v_mul_f32_e32 v73, v103, v103
	v_fmac_f32_e32 v68, v98, v98
	v_fmac_f32_e32 v69, v100, v100
	v_and_b32_e32 v57, 0xffff0000, v57
	v_and_b32_e32 v59, 0xffff0000, v59
	v_lshlrev_b32_e32 v60, 16, v61
	v_lshlrev_b32_e32 v104, 16, v62
	v_and_b32_e32 v109, 0xffff0000, v64
	v_and_b32_e32 v108, 0xffff0000, v66
	v_lshlrev_b32_e32 v70, 16, v84
	v_and_b32_e32 v114, 0xffff0000, v84
	v_mul_f32_e32 v84, v105, v105
	v_fmac_f32_e32 v73, v102, v102
	v_fmac_f32_e32 v68, v56, v56
	v_fmac_f32_e32 v69, v58, v58
	v_and_b32_e32 v61, 0xffff0000, v61
	v_lshlrev_b32_e32 v62, 16, v63
	v_lshlrev_b32_e32 v107, 16, v64
	v_lshlrev_b32_e32 v106, 16, v66
	v_lshlrev_b32_e32 v111, 16, v65
	v_and_b32_e32 v113, 0xffff0000, v65
	v_pk_mul_f32 v[64:65], v[108:109], v[108:109]
	v_fmac_f32_e32 v84, v104, v104
	v_fmac_f32_e32 v73, v60, v60
	v_fmac_f32_e32 v68, v57, v57
	v_fmac_f32_e32 v69, v59, v59
	v_and_b32_e32 v63, 0xffff0000, v63
	v_lshlrev_b32_e32 v110, 16, v67
	v_pk_fma_f32 v[64:65], v[106:107], v[106:107], v[64:65]
	v_fmac_f32_e32 v84, v62, v62
	v_fmac_f32_e32 v73, v61, v61
	v_add_f32_e32 v68, v68, v69
	v_and_b32_e32 v112, 0xffff0000, v67
	v_pk_mul_f32 v[66:67], v[114:115], v[114:115]
	v_pk_fma_f32 v[64:65], v[110:111], v[110:111], v[64:65]
	v_fmac_f32_e32 v84, v63, v63
	v_add_f32_e32 v68, v68, v73
	v_lshlrev_b32_e32 v116, 16, v85
	v_pk_fma_f32 v[66:67], v[70:71], v[70:71], v[66:67]
	v_pk_fma_f32 v[64:65], v[112:113], v[112:113], v[64:65]
	v_add_f32_e32 v68, v68, v84
	v_and_b32_e32 v118, 0xffff0000, v85
	v_pk_fma_f32 v[66:67], v[116:117], v[116:117], v[66:67]
	v_add_f32_e32 v64, v68, v64
	v_pk_fma_f32 v[66:67], v[118:119], v[118:119], v[66:67]
	v_add_f32_e32 v64, v64, v65
	v_add_f32_e32 v64, v64, v66
	v_add_f32_e32 v64, v64, v67
	ds_bpermute_b32 v65, v83, v64
	v_mov_b32_e32 v124, v106
	v_mov_b32_e32 v126, v110
	v_mov_b32_e32 v127, v112
	v_mov_b32_e32 v112, v111
	s_waitcnt lgkmcnt(0)
	v_add_f32_e32 v64, v64, v65
	ds_bpermute_b32 v65, v132, v64
	s_waitcnt lgkmcnt(0)
	v_add_f32_e32 v64, v64, v65
	ds_bpermute_b32 v65, v133, v64
	s_waitcnt lgkmcnt(0)
	v_add_f32_e32 v66, v64, v65
	v_add_u32_e32 v64, 1, v72
	ds_bpermute_b32 v67, v134, v66
	v_ashrrev_i32_e32 v65, 31, v64
	v_lshlrev_b64 v[84:85], 12, v[64:65]
	v_lshl_add_u64 v[68:69], v[74:75], 0, v[84:85]
	global_load_dwordx2 v[120:121], v[68:69], off sc1
	global_load_dwordx2 v[122:123], v[68:69], off offset:512 sc1
	global_load_dwordx2 v[138:139], v[68:69], off offset:1024 sc1
	global_load_dwordx2 v[140:141], v[68:69], off offset:1536 sc1
	s_waitcnt lgkmcnt(0)
	v_add_f32_e32 v66, v66, v67
	ds_bpermute_b32 v67, v135, v66
	v_add_u32_e32 v72, s13, v72
	s_waitcnt lgkmcnt(0)
	v_add_f32_e32 v73, v66, v67
	global_load_dwordx2 v[142:143], v[68:69], off offset:2048 sc1
	global_load_dwordx2 v[144:145], v[68:69], off offset:2560 sc1
	global_load_dwordx2 v[66:67], v[68:69], off offset:3072 sc1
	s_nop 0
	global_load_dwordx2 v[68:69], v[68:69], off offset:3584 sc1
	ds_bpermute_b32 v125, v136, v73
	s_waitcnt lgkmcnt(0)
	v_add_f32_e32 v73, v73, v125
	v_fmamk_f32 v73, v73, 0x3a000000, v82
	v_mul_f32_e32 v106, 0x4b800000, v73
	v_cmp_gt_f32_e32 vcc, s14, v73
	v_mov_b32_e32 v125, v108
	v_mov_b32_e32 v108, v107
	v_cndmask_b32_e32 v73, v73, v106, vcc
	v_rsq_f32_e32 v73, v73
	s_waitcnt vmcnt(7)
	v_and_b32_e32 v164, 0xffff0000, v120
	v_mul_f32_e32 v106, 0x45800000, v73
	v_cndmask_b32_e32 v106, v73, v106, vcc
	v_pk_mul_f32 v[98:99], v[98:99], v[106:107] op_sel_hi:[1,0]
	v_pk_mul_f32 v[102:103], v[102:103], v[106:107] op_sel_hi:[1,0]
	v_pk_mul_f32 v[124:125], v[124:125], v[106:107] op_sel_hi:[1,0]
	v_pk_mul_f32 v[56:57], v[56:57], v[106:107] op_sel_hi:[1,0]
	v_pk_mul_f32 v[128:129], v[60:61], v[106:107] op_sel_hi:[1,0]
	v_pk_mul_f32 v[126:127], v[126:127], v[106:107] op_sel_hi:[1,0]
	v_pk_fma_f32 v[60:61], v[0:1], v[98:99], v[52:53]
	v_pk_fma_f32 v[52:53], v[8:9], v[102:103], v[44:45]
	v_pk_fma_f32 v[44:45], v[16:17], v[124:125], v[36:37]
	v_pk_mul_f32 v[36:37], v[108:109], v[106:107] op_sel_hi:[1,0]
	v_pk_mul_f32 v[130:131], v[62:63], v[106:107] op_sel_hi:[1,0]
	v_pk_fma_f32 v[62:63], v[2:3], v[56:57], v[54:55]
	v_pk_fma_f32 v[54:55], v[10:11], v[128:129], v[46:47]
	v_pk_fma_f32 v[46:47], v[18:19], v[126:127], v[38:39]
	v_pk_mul_f32 v[38:39], v[112:113], v[106:107] op_sel_hi:[1,0]
	v_pk_fma_f32 v[32:33], v[20:21], v[36:37], v[32:33]
	v_pk_mul_f32 v[100:101], v[100:101], v[106:107] op_sel_hi:[1,0]
	v_pk_fma_f32 v[34:35], v[22:23], v[38:39], v[34:35]
	v_mov_b32_e32 v38, v33
	v_mov_b32_e32 v39, v45
	v_pk_mul_f32 v[58:59], v[58:59], v[106:107] op_sel_hi:[1,0]
	v_pk_fma_f32 v[56:57], v[4:5], v[100:101], v[48:49]
	v_mov_b32_e32 v36, v32
	v_mov_b32_e32 v37, v44
	v_pk_mul_f32 v[38:39], v[38:39], v[38:39]
	v_pk_fma_f32 v[58:59], v[6:7], v[58:59], v[50:51]
	v_pk_fma_f32 v[50:51], v[14:15], v[130:131], v[42:43]
	v_pk_fma_f32 v[36:37], v[36:37], v[36:37], v[38:39]
	v_mov_b32_e32 v38, v34
	v_mov_b32_e32 v39, v46
	s_waitcnt vmcnt(6)
	v_and_b32_e32 v130, 0xffff0000, v122
	v_mov_b32_e32 v165, v61
	v_mov_b32_e32 v131, v57
	v_pk_fma_f32 v[36:37], v[38:39], v[38:39], v[36:37]
	v_mov_b32_e32 v38, v35
	v_mov_b32_e32 v39, v47
	v_lshlrev_b32_e32 v162, 16, v120
	v_lshlrev_b32_e32 v126, 16, v122
	v_mov_b32_e32 v163, v60
	v_pk_mul_f32 v[100:101], v[164:165], v[164:165]
	v_mov_b32_e32 v127, v56
	v_pk_mul_f32 v[102:103], v[130:131], v[130:131]
	v_pk_mul_f32 v[104:105], v[104:105], v[106:107] op_sel_hi:[1,0]
	v_pk_fma_f32 v[146:147], v[38:39], v[38:39], v[36:37]
	v_mov_b32_e32 v36, v70
	v_mov_b32_e32 v37, v114
	v_mov_b32_e32 v114, v71
	v_lshlrev_b32_e32 v166, 16, v121
	v_lshlrev_b32_e32 v124, 16, v123
	v_pk_fma_f32 v[100:101], v[162:163], v[162:163], v[100:101]
	v_mov_b32_e32 v167, v62
	v_pk_fma_f32 v[102:103], v[126:127], v[126:127], v[102:103]
	v_mov_b32_e32 v125, v58
	v_pk_fma_f32 v[48:49], v[12:13], v[104:105], v[40:41]
	v_pk_mul_f32 v[36:37], v[36:37], v[106:107] op_sel_hi:[1,0]
	v_pk_mul_f32 v[40:41], v[114:115], v[106:107] op_sel_hi:[1,0]
	v_and_b32_e32 v168, 0xffff0000, v121
	v_and_b32_e32 v128, 0xffff0000, v123
	v_pk_fma_f32 v[100:101], v[166:167], v[166:167], v[100:101]
	v_mov_b32_e32 v169, v63
	v_pk_fma_f32 v[102:103], v[124:125], v[124:125], v[102:103]
	v_mov_b32_e32 v129, v59
	v_mov_b32_e32 v38, v116
	v_mov_b32_e32 v39, v118
	v_pk_fma_f32 v[36:37], v[24:25], v[36:37], v[90:91]
	v_mov_b32_e32 v118, v117
	v_pk_fma_f32 v[40:41], v[28:29], v[40:41], v[94:95]
	s_waitcnt vmcnt(5)
	v_and_b32_e32 v122, 0xffff0000, v138
	v_pk_fma_f32 v[100:101], v[168:169], v[168:169], v[100:101]
	v_pk_fma_f32 v[102:103], v[128:129], v[128:129], v[102:103]
	v_mov_b32_e32 v123, v53
	v_pk_mul_f32 v[38:39], v[38:39], v[106:107] op_sel_hi:[1,0]
	v_pk_mul_f32 v[42:43], v[118:119], v[106:107] op_sel_hi:[1,0]
	v_mov_b32_e32 v90, v41
	v_mov_b32_e32 v91, v37
	v_lshlrev_b32_e32 v118, 16, v138
	v_pk_add_f32 v[100:101], v[100:101], v[102:103]
	v_mov_b32_e32 v119, v52
	v_pk_mul_f32 v[102:103], v[122:123], v[122:123]
	v_pk_fma_f32 v[38:39], v[26:27], v[38:39], v[92:93]
	v_pk_fma_f32 v[42:43], v[30:31], v[42:43], v[96:97]
	v_mov_b32_e32 v70, v40
	v_mov_b32_e32 v71, v36
	v_pk_mul_f32 v[90:91], v[90:91], v[90:91]
	v_lshlrev_b32_e32 v116, 16, v139
	v_pk_fma_f32 v[102:103], v[118:119], v[118:119], v[102:103]
	v_mov_b32_e32 v117, v54
	v_pk_fma_f32 v[70:71], v[70:71], v[70:71], v[90:91]
	v_mov_b32_e32 v90, v42
	v_mov_b32_e32 v91, v38
	v_and_b32_e32 v120, 0xffff0000, v139
	v_pk_fma_f32 v[102:103], v[116:117], v[116:117], v[102:103]
	v_mov_b32_e32 v121, v55
	v_pk_fma_f32 v[70:71], v[90:91], v[90:91], v[70:71]
	v_mov_b32_e32 v90, v43
	v_mov_b32_e32 v91, v39
	s_waitcnt vmcnt(4)
	v_and_b32_e32 v114, 0xffff0000, v140
	s_waitcnt vmcnt(2)
	v_and_b32_e32 v95, 0xffff0000, v144
	v_and_b32_e32 v94, 0xffff0000, v142
	v_pk_fma_f32 v[102:103], v[120:121], v[120:121], v[102:103]
	v_mov_b32_e32 v115, v49
	v_pk_fma_f32 v[70:71], v[90:91], v[90:91], v[70:71]
	v_lshlrev_b32_e32 v110, 16, v140
	v_lshlrev_b32_e32 v91, 16, v144
	v_lshlrev_b32_e32 v90, 16, v142
	v_pk_mul_f32 v[92:93], v[94:95], v[94:95]
	v_pk_add_f32 v[100:101], v[102:103], v[100:101]
	v_mov_b32_e32 v111, v48
	v_pk_mul_f32 v[102:103], v[114:115], v[114:115]
	v_lshlrev_b32_e32 v108, 16, v141
	v_lshlrev_b32_e32 v97, 16, v145
	v_lshlrev_b32_e32 v96, 16, v143
	v_pk_fma_f32 v[92:93], v[90:91], v[90:91], v[92:93]
	v_pk_fma_f32 v[102:103], v[110:111], v[110:111], v[102:103]
	v_mov_b32_e32 v109, v50
	v_and_b32_e32 v112, 0xffff0000, v141
	v_and_b32_e32 v99, 0xffff0000, v145
	v_and_b32_e32 v98, 0xffff0000, v143
	v_pk_fma_f32 v[92:93], v[96:97], v[96:97], v[92:93]
	v_pk_fma_f32 v[102:103], v[108:109], v[108:109], v[102:103]
	v_mov_b32_e32 v113, v51
	v_pk_fma_f32 v[92:93], v[98:99], v[98:99], v[92:93]
	v_pk_fma_f32 v[102:103], v[112:113], v[112:113], v[102:103]
	s_waitcnt vmcnt(1)
	v_lshlrev_b32_e32 v104, 16, v67
	v_pk_add_f32 v[100:101], v[102:103], v[100:101]
	v_mov_b32_e32 v102, v92
	v_mov_b32_e32 v103, v147
	v_pk_add_f32 v[138:139], v[100:101], v[102:103]
	s_waitcnt vmcnt(0)
	v_and_b32_e32 v103, 0xffff0000, v68
	v_and_b32_e32 v102, 0xffff0000, v66
	v_lshlrev_b32_e32 v101, 16, v68
	v_lshlrev_b32_e32 v100, 16, v66
	v_and_b32_e32 v106, 0xffff0000, v67
	v_pk_mul_f32 v[66:67], v[102:103], v[102:103]
	v_lshlrev_b32_e32 v105, 16, v69
	v_pk_fma_f32 v[66:67], v[100:101], v[100:101], v[66:67]
	v_and_b32_e32 v107, 0xffff0000, v69
	v_pk_fma_f32 v[66:67], v[104:105], v[104:105], v[66:67]
	v_pk_mov_b32 v[68:69], v[92:93], v[146:147] op_sel:[1,0]
	v_pk_fma_f32 v[66:67], v[106:107], v[106:107], v[66:67]
	v_pk_add_f32 v[68:69], v[138:139], v[68:69]
	v_mov_b32_e32 v92, v66
	v_mov_b32_e32 v93, v71
	v_pk_add_f32 v[68:69], v[68:69], v[92:93]
	v_lshlrev_b64 v[92:93], 13, v[64:65]
	v_lshl_add_u64 v[64:65], v[80:81], 0, v[92:93]
	v_pk_mov_b32 v[66:67], v[66:67], v[70:71] op_sel:[1,0]
	global_load_dwordx4 v[138:141], v[64:65], off nt
	global_load_dwordx4 v[142:145], v[64:65], off offset:1024 nt
	global_load_dwordx4 v[146:149], v[64:65], off offset:2048 nt
	global_load_dwordx4 v[150:153], v[64:65], off offset:3072 nt
	v_pk_add_f32 v[66:67], v[68:69], v[66:67]
	ds_bpermute_b32 v69, v83, v67
	ds_bpermute_b32 v68, v83, v66
	v_add_co_u32_e32 v64, vcc, s3, v64
	v_mov_b32_e32 v163, v164
	s_nop 0
	v_addc_co_u32_e32 v65, vcc, 0, v65, vcc
	s_waitcnt lgkmcnt(0)
	v_pk_add_f32 v[66:67], v[66:67], v[68:69]
	ds_bpermute_b32 v69, v132, v67
	ds_bpermute_b32 v68, v132, v66
	v_mov_b32_e32 v127, v130
	v_mov_b32_e32 v167, v168
	v_mov_b32_e32 v125, v128
	v_mov_b32_e32 v119, v122
	s_waitcnt lgkmcnt(0)
	v_pk_add_f32 v[66:67], v[66:67], v[68:69]
	ds_bpermute_b32 v69, v133, v67
	ds_bpermute_b32 v68, v133, v66
	v_mov_b32_e32 v117, v120
	v_mov_b32_e32 v111, v114
	v_mov_b32_e32 v109, v112
	s_waitcnt lgkmcnt(0)
	v_pk_add_f32 v[170:171], v[66:67], v[68:69]
	global_load_dwordx4 v[154:157], v[64:65], off nt
	global_load_dwordx4 v[158:161], v[64:65], off offset:1024 nt
	global_load_dwordx4 v[68:71], v[64:65], off offset:2048 nt
	s_nop 0
	global_load_dwordx4 v[64:67], v[64:65], off offset:3072 nt
	ds_bpermute_b32 v173, v134, v171
	ds_bpermute_b32 v172, v134, v170
	global_store_dwordx4 v[88:89], v[60:63], off nt
	global_store_dwordx4 v[88:89], v[56:59], off offset:1024 nt
	global_store_dwordx4 v[88:89], v[52:55], off offset:2048 nt
	global_store_dwordx4 v[88:89], v[48:51], off offset:3072 nt
	v_add_co_u32_e32 v88, vcc, s3, v88
	s_waitcnt lgkmcnt(0)
	v_pk_add_f32 v[170:171], v[170:171], v[172:173]
	ds_bpermute_b32 v173, v135, v171
	ds_bpermute_b32 v172, v135, v170
	v_addc_co_u32_e32 v89, vcc, 0, v89, vcc
	global_store_dwordx4 v[88:89], v[44:47], off nt
	global_store_dwordx4 v[88:89], v[32:35], off offset:1024 nt
	global_store_dwordx4 v[88:89], v[36:39], off offset:2048 nt
	global_store_dwordx4 v[88:89], v[40:43], off offset:3072 nt
	s_waitcnt lgkmcnt(0)
	v_pk_add_f32 v[170:171], v[170:171], v[172:173]
	ds_bpermute_b32 v173, v136, v171
	ds_bpermute_b32 v172, v136, v170
	s_waitcnt lgkmcnt(0)
	v_pk_add_f32 v[170:171], v[170:171], v[172:173]
	s_nop 0
	v_pk_fma_f32 v[170:171], v[170:171], s[12:13], v[82:83] op_sel_hi:[1,0,0]
	s_nop 0
	v_mul_f32_e32 v73, 0x4b800000, v171
	v_cmp_gt_f32_e32 vcc, s14, v171
	s_nop 1
	v_cndmask_b32_e32 v73, v171, v73, vcc
	v_rsq_f32_e32 v73, v73
	s_nop 0
	v_mul_f32_e32 v88, 0x45800000, v73
	v_cndmask_b32_e32 v88, v73, v88, vcc
	v_pk_mul_f32 v[44:45], v[44:45], v[88:89] op_sel_hi:[1,0]
	v_pk_mul_f32 v[48:49], v[48:49], v[88:89] op_sel_hi:[1,0]
	v_pk_mul_f32 v[50:51], v[50:51], v[88:89] op_sel_hi:[1,0]
	v_cvt_pk_bf16_f32 v44, v44, v45
	v_mul_f32_e32 v45, 0x4b800000, v170
	v_cmp_gt_f32_e32 vcc, s14, v170
	v_cvt_pk_bf16_f32 v48, v48, v49
	v_cvt_pk_bf16_f32 v49, v50, v51
	v_cndmask_b32_e32 v45, v170, v45, vcc
	global_store_dwordx2 v[86:87], v[48:49], off offset:1536
	v_rsq_f32_e32 v48, v45
	v_pk_mul_f32 v[46:47], v[46:47], v[88:89] op_sel_hi:[1,0]
	v_pk_mul_f32 v[52:53], v[52:53], v[88:89] op_sel_hi:[1,0]
	v_cvt_pk_bf16_f32 v45, v46, v47
	global_store_dwordx2 v[86:87], v[44:45], off offset:2048
	v_mul_f32_e32 v44, 0x45800000, v48
	v_cndmask_b32_e32 v170, v48, v44, vcc
	v_pk_mul_f32 v[54:55], v[54:55], v[88:89] op_sel_hi:[1,0]
	v_pk_mul_f32 v[44:45], v[162:163], v[170:171] op_sel_hi:[1,0]
	v_pk_mul_f32 v[48:49], v[126:127], v[170:171] op_sel_hi:[1,0]
	v_cvt_pk_bf16_f32 v52, v52, v53
	v_cvt_pk_bf16_f32 v53, v54, v55
	s_waitcnt vmcnt(17)
	v_pk_fma_f32 v[44:45], v[0:1], v[44:45], v[138:139]
	s_waitcnt vmcnt(16)
	v_pk_fma_f32 v[48:49], v[4:5], v[48:49], v[142:143]
	global_store_dwordx2 v[86:87], v[52:53], off offset:1024
	v_pk_mul_f32 v[46:47], v[166:167], v[170:171] op_sel_hi:[1,0]
	v_mul_f32_e32 v52, v45, v45
	v_pk_mul_f32 v[50:51], v[124:125], v[170:171] op_sel_hi:[1,0]
	v_mul_f32_e32 v53, v49, v49
	v_pk_fma_f32 v[46:47], v[2:3], v[46:47], v[140:141]
	v_fmac_f32_e32 v52, v44, v44
	v_pk_fma_f32 v[50:51], v[6:7], v[50:51], v[144:145]
	v_fmac_f32_e32 v53, v48, v48
	v_pk_mul_f32 v[56:57], v[56:57], v[88:89] op_sel_hi:[1,0]
	v_pk_mul_f32 v[58:59], v[58:59], v[88:89] op_sel_hi:[1,0]
	v_fmac_f32_e32 v52, v46, v46
	v_fmac_f32_e32 v53, v50, v50
	v_cvt_pk_bf16_f32 v56, v56, v57
	v_cvt_pk_bf16_f32 v57, v58, v59
	v_fmac_f32_e32 v52, v47, v47
	v_fmac_f32_e32 v53, v51, v51
	global_store_dwordx2 v[86:87], v[56:57], off offset:512
	v_add_f32_e32 v56, v52, v53
	v_pk_mul_f32 v[52:53], v[118:119], v[170:171] op_sel_hi:[1,0]
	v_pk_mul_f32 v[54:55], v[116:117], v[170:171] op_sel_hi:[1,0]
	s_waitcnt vmcnt(17)
	v_pk_fma_f32 v[52:53], v[8:9], v[52:53], v[146:147]
	v_pk_fma_f32 v[54:55], v[10:11], v[54:55], v[148:149]
	v_mul_f32_e32 v57, v53, v53
	v_fmac_f32_e32 v57, v52, v52
	v_pk_mul_f32 v[60:61], v[60:61], v[88:89] op_sel_hi:[1,0]
	v_pk_mul_f32 v[62:63], v[62:63], v[88:89] op_sel_hi:[1,0]
	v_fmac_f32_e32 v57, v54, v54
	v_cvt_pk_bf16_f32 v60, v60, v61
	v_cvt_pk_bf16_f32 v61, v62, v63
	v_fmac_f32_e32 v57, v55, v55
	global_store_dwordx2 v[86:87], v[60:61], off
	v_add_f32_e32 v60, v57, v56
	v_pk_mul_f32 v[56:57], v[110:111], v[170:171] op_sel_hi:[1,0]
	v_pk_mul_f32 v[58:59], v[108:109], v[170:171] op_sel_hi:[1,0]
	s_waitcnt vmcnt(17)
	v_pk_fma_f32 v[56:57], v[12:13], v[56:57], v[150:151]
	v_pk_fma_f32 v[58:59], v[14:15], v[58:59], v[152:153]
	v_mul_f32_e32 v61, v57, v57
	v_fmac_f32_e32 v61, v56, v56
	v_fmac_f32_e32 v61, v58, v58
	v_fmac_f32_e32 v61, v59, v59
	v_add_f32_e32 v73, v61, v60
	v_mov_b32_e32 v60, v90
	v_mov_b32_e32 v61, v94
	v_mov_b32_e32 v63, v98
	v_mov_b32_e32 v94, v91
	v_mov_b32_e32 v98, v97
	v_pk_mul_f32 v[60:61], v[60:61], v[170:171] op_sel_hi:[1,0]
	v_pk_mul_f32 v[90:91], v[94:95], v[170:171] op_sel_hi:[1,0]
	v_pk_mul_f32 v[94:95], v[98:99], v[170:171] op_sel_hi:[1,0]
	v_mov_b32_e32 v62, v96
	s_waitcnt vmcnt(16)
	v_pk_fma_f32 v[60:61], v[16:17], v[60:61], v[154:155]
	s_waitcnt vmcnt(15)
	v_pk_fma_f32 v[96:97], v[22:23], v[94:95], v[160:161]
	v_pk_fma_f32 v[94:95], v[20:21], v[90:91], v[158:159]
	v_pk_mul_f32 v[62:63], v[62:63], v[170:171] op_sel_hi:[1,0]
	v_mov_b32_e32 v98, v95
	v_mov_b32_e32 v99, v61
	v_pk_fma_f32 v[62:63], v[18:19], v[62:63], v[156:157]
	v_mov_b32_e32 v90, v94
	v_mov_b32_e32 v91, v60
	v_pk_mul_f32 v[98:99], v[98:99], v[98:99]
	s_nop 0
	v_pk_fma_f32 v[90:91], v[90:91], v[90:91], v[98:99]
	v_mov_b32_e32 v98, v96
	v_mov_b32_e32 v99, v62
	v_pk_fma_f32 v[90:91], v[98:99], v[98:99], v[90:91]
	v_mov_b32_e32 v98, v97
	v_mov_b32_e32 v99, v63
	v_pk_fma_f32 v[90:91], v[98:99], v[98:99], v[90:91]
	v_mov_b32_e32 v98, v104
	v_add_f32_e32 v73, v91, v73
	v_add_f32_e32 v73, v90, v73
	v_mov_b32_e32 v90, v100
	v_mov_b32_e32 v91, v102
	v_pk_mul_f32 v[90:91], v[90:91], v[170:171] op_sel_hi:[1,0]
	v_mov_b32_e32 v99, v106
	v_mov_b32_e32 v102, v101
	v_pk_mul_f32 v[98:99], v[98:99], v[170:171] op_sel_hi:[1,0]
	s_waitcnt vmcnt(14)
	v_pk_fma_f32 v[68:69], v[24:25], v[90:91], v[68:69]
	v_pk_mul_f32 v[90:91], v[102:103], v[170:171] op_sel_hi:[1,0]
	v_mov_b32_e32 v106, v105
	v_pk_fma_f32 v[70:71], v[26:27], v[98:99], v[70:71]
	v_pk_mul_f32 v[98:99], v[106:107], v[170:171] op_sel_hi:[1,0]
	s_waitcnt vmcnt(13)
	v_pk_fma_f32 v[64:65], v[28:29], v[90:91], v[64:65]
	v_pk_fma_f32 v[66:67], v[30:31], v[98:99], v[66:67]
	v_mov_b32_e32 v98, v65
	v_mov_b32_e32 v99, v69
	v_mov_b32_e32 v90, v64
	v_mov_b32_e32 v91, v68
	v_pk_mul_f32 v[98:99], v[98:99], v[98:99]
	s_nop 0
	v_pk_fma_f32 v[90:91], v[90:91], v[90:91], v[98:99]
	v_mov_b32_e32 v98, v66
	v_mov_b32_e32 v99, v70
	v_pk_fma_f32 v[90:91], v[98:99], v[98:99], v[90:91]
	v_mov_b32_e32 v98, v67
	v_mov_b32_e32 v99, v71
	v_pk_fma_f32 v[90:91], v[98:99], v[98:99], v[90:91]
	s_nop 0
	v_add_f32_e32 v73, v91, v73
	v_add_f32_e32 v73, v90, v73
	ds_bpermute_b32 v89, v83, v73
	s_waitcnt lgkmcnt(0)
	v_add_f32_e32 v73, v73, v89
	v_pk_mul_f32 v[32:33], v[32:33], v[88:89] op_sel_hi:[1,0]
	v_pk_mul_f32 v[34:35], v[34:35], v[88:89] op_sel_hi:[1,0]
	ds_bpermute_b32 v89, v132, v73
	v_cvt_pk_bf16_f32 v32, v32, v33
	v_cvt_pk_bf16_f32 v33, v34, v35
	global_store_dwordx2 v[86:87], v[32:33], off offset:2560
	s_waitcnt lgkmcnt(0)
	v_pk_mul_f32 v[32:33], v[36:37], v[88:89] op_sel_hi:[1,0]
	v_add_f32_e32 v36, v73, v89
	ds_bpermute_b32 v37, v133, v36
	v_pk_mul_f32 v[34:35], v[38:39], v[88:89] op_sel_hi:[1,0]
	v_cvt_pk_bf16_f32 v32, v32, v33
	v_cvt_pk_bf16_f32 v33, v34, v35
	global_store_dwordx2 v[86:87], v[32:33], off offset:3072
	s_waitcnt lgkmcnt(0)
	v_add_f32_e32 v36, v36, v37
	ds_bpermute_b32 v37, v134, v36
	v_pk_mul_f32 v[32:33], v[40:41], v[88:89] op_sel_hi:[1,0]
	v_pk_mul_f32 v[34:35], v[42:43], v[88:89] op_sel_hi:[1,0]
	v_cvt_pk_bf16_f32 v32, v32, v33
	v_cvt_pk_bf16_f32 v33, v34, v35
	s_waitcnt lgkmcnt(0)
	v_add_f32_e32 v34, v36, v37
	ds_bpermute_b32 v35, v135, v34
	global_store_dwordx2 v[86:87], v[32:33], off offset:3584
	v_lshl_add_u64 v[32:33], v[76:77], 0, v[92:93]
	global_store_dwordx4 v[32:33], v[44:47], off nt
	global_store_dwordx4 v[32:33], v[48:51], off offset:1024 nt
	global_store_dwordx4 v[32:33], v[52:55], off offset:2048 nt
	global_store_dwordx4 v[32:33], v[56:59], off offset:3072 nt
	v_add_co_u32_e32 v32, vcc, s3, v32
	s_waitcnt lgkmcnt(0)
	v_add_f32_e32 v34, v34, v35
	ds_bpermute_b32 v35, v136, v34
	v_addc_co_u32_e32 v33, vcc, 0, v33, vcc
	global_store_dwordx4 v[32:33], v[60:63], off nt
	global_store_dwordx4 v[32:33], v[94:97], off offset:1024 nt
	global_store_dwordx4 v[32:33], v[68:71], off offset:2048 nt
	global_store_dwordx4 v[32:33], v[64:67], off offset:3072 nt
	s_waitcnt lgkmcnt(0)
	v_add_f32_e32 v34, v34, v35
	v_fmamk_f32 v34, v34, 0x3a000000, v82
	v_mul_f32_e32 v35, 0x4b800000, v34
	v_cmp_gt_f32_e32 vcc, s14, v34
	s_nop 1
	v_cndmask_b32_e32 v34, v34, v35, vcc
	v_rsq_f32_e32 v34, v34
	s_nop 0
	v_mul_f32_e32 v32, 0x45800000, v34
	v_cndmask_b32_e32 v32, v34, v32, vcc
	v_pk_mul_f32 v[36:37], v[44:45], v[32:33] op_sel_hi:[1,0]
	v_pk_mul_f32 v[38:39], v[46:47], v[32:33] op_sel_hi:[1,0]
	v_lshl_add_u64 v[34:35], v[78:79], 0, v[84:85]
	v_cvt_pk_bf16_f32 v36, v36, v37
	v_cvt_pk_bf16_f32 v37, v38, v39
	global_store_dwordx2 v[34:35], v[36:37], off
	v_pk_mul_f32 v[36:37], v[48:49], v[32:33] op_sel_hi:[1,0]
	v_pk_mul_f32 v[38:39], v[50:51], v[32:33] op_sel_hi:[1,0]
	v_cvt_pk_bf16_f32 v36, v36, v37
	v_cvt_pk_bf16_f32 v37, v38, v39
	global_store_dwordx2 v[34:35], v[36:37], off offset:512
	v_pk_mul_f32 v[36:37], v[52:53], v[32:33] op_sel_hi:[1,0]
	v_pk_mul_f32 v[38:39], v[54:55], v[32:33] op_sel_hi:[1,0]
	v_cvt_pk_bf16_f32 v36, v36, v37
	v_cvt_pk_bf16_f32 v37, v38, v39
	global_store_dwordx2 v[34:35], v[36:37], off offset:1024
	v_pk_mul_f32 v[36:37], v[56:57], v[32:33] op_sel_hi:[1,0]
	v_pk_mul_f32 v[38:39], v[58:59], v[32:33] op_sel_hi:[1,0]
	v_cvt_pk_bf16_f32 v36, v36, v37
	v_cvt_pk_bf16_f32 v37, v38, v39
	global_store_dwordx2 v[34:35], v[36:37], off offset:1536
	v_pk_mul_f32 v[36:37], v[60:61], v[32:33] op_sel_hi:[1,0]
	v_pk_mul_f32 v[38:39], v[62:63], v[32:33] op_sel_hi:[1,0]
	v_cvt_pk_bf16_f32 v36, v36, v37
	v_cvt_pk_bf16_f32 v37, v38, v39
	global_store_dwordx2 v[34:35], v[36:37], off offset:2048
	v_pk_mul_f32 v[36:37], v[94:95], v[32:33] op_sel_hi:[1,0]
	v_pk_mul_f32 v[38:39], v[96:97], v[32:33] op_sel_hi:[1,0]
	v_cvt_pk_bf16_f32 v36, v36, v37
	v_cvt_pk_bf16_f32 v37, v38, v39
	global_store_dwordx2 v[34:35], v[36:37], off offset:2560
	v_pk_mul_f32 v[36:37], v[68:69], v[32:33] op_sel_hi:[1,0]
	v_pk_mul_f32 v[38:39], v[70:71], v[32:33] op_sel_hi:[1,0]
	v_cvt_pk_bf16_f32 v36, v36, v37
	v_cvt_pk_bf16_f32 v37, v38, v39
	global_store_dwordx2 v[34:35], v[36:37], off offset:3072
	v_pk_mul_f32 v[36:37], v[64:65], v[32:33] op_sel_hi:[1,0]
	v_pk_mul_f32 v[32:33], v[66:67], v[32:33] op_sel_hi:[1,0]
	v_cmp_lt_i32_e32 vcc, s15, v72
	v_cvt_pk_bf16_f32 v36, v36, v37
	v_cvt_pk_bf16_f32 v37, v32, v33
	s_or_b64 s[10:11], vcc, s[10:11]
	global_store_dwordx2 v[34:35], v[36:37], off offset:3584
	s_andn2_b64 exec, exec, s[10:11]
	s_cbranch_execnz .LBB0_756

.LBB0_1491:
	v_ashrrev_i32_e32 v49, 31, v48
	v_lshlrev_b64 v[32:33], 12, v[48:49]
	v_lshl_add_u64 v[32:33], v[50:51], 0, v[32:33]
	v_add_u32_e32 v44, 1, v48
	global_load_dwordx2 v[46:47], v[32:33], off offset:2560 sc1
	global_load_dwordx2 v[56:57], v[32:33], off offset:2048 sc1
	global_load_dwordx2 v[58:59], v[32:33], off offset:3584 sc1
	global_load_dwordx2 v[60:61], v[32:33], off offset:3072 sc1
	global_load_dwordx2 v[62:63], v[32:33], off sc1
	global_load_dwordx2 v[76:77], v[32:33], off offset:512 sc1
	global_load_dwordx2 v[104:105], v[32:33], off offset:1024 sc1
	v_ashrrev_i32_e32 v45, 31, v44
	v_lshlrev_b64 v[34:35], 12, v[44:45]
	v_lshl_add_u64 v[64:65], v[50:51], 0, v[34:35]
	global_load_dwordx2 v[106:107], v[64:65], off offset:2560 sc1
	global_load_dwordx2 v[108:109], v[64:65], off offset:2048 sc1
	global_load_dwordx2 v[110:111], v[64:65], off sc1
	global_load_dwordx2 v[112:113], v[64:65], off offset:512 sc1
	global_load_dwordx2 v[114:115], v[64:65], off offset:1024 sc1
	global_load_dwordx2 v[122:123], v[64:65], off offset:1536 sc1
	global_load_dwordx2 v[120:121], v[32:33], off offset:1536 sc1
	v_lshlrev_b64 v[32:33], 13, v[48:49]
	v_lshl_add_u64 v[100:101], v[52:53], 0, v[32:33]
	global_load_dwordx4 v[40:43], v[100:101], off nt
	global_load_dwordx4 v[36:39], v[100:101], off offset:1024 nt
	global_load_dwordx4 v[32:35], v[100:101], off offset:2048 nt
	global_load_dwordx2 v[130:131], v[64:65], off offset:3072 sc1
	global_load_dwordx2 v[132:133], v[64:65], off offset:3584 sc1
	v_add_co_u32_e32 v178, vcc, s3, v100
	v_lshlrev_b64 v[44:45], 13, v[44:45]
	s_nop 0
	v_addc_co_u32_e32 v179, vcc, 0, v101, vcc
	v_lshl_add_u64 v[180:181], v[52:53], 0, v[44:45]
	v_add_u32_e32 v48, s4, v48
	s_waitcnt vmcnt(0)
	v_and_b32_e32 v83, 0xffff0000, v46
	v_lshlrev_b32_e32 v78, 16, v56
	v_and_b32_e32 v67, 0xffff0000, v58
	v_and_b32_e32 v66, 0xffff0000, v60
	v_and_b32_e32 v82, 0xffff0000, v56
	v_lshlrev_b32_e32 v94, 16, v57
	v_and_b32_e32 v98, 0xffff0000, v57
	v_lshlrev_b32_e32 v65, 16, v58
	v_lshlrev_b32_e32 v64, 16, v60
	v_pk_mul_f32 v[116:117], v[66:67], v[66:67]
	v_and_b32_e32 v57, 0xffff0000, v106
	v_and_b32_e32 v56, 0xffff0000, v108
	v_lshlrev_b32_e32 v69, 16, v59
	v_lshlrev_b32_e32 v68, 16, v61
	v_and_b32_e32 v71, 0xffff0000, v59
	v_and_b32_e32 v70, 0xffff0000, v61
	v_lshlrev_b32_e32 v73, 16, v62
	v_and_b32_e32 v81, 0xffff0000, v62
	v_lshlrev_b32_e32 v87, 16, v63
	v_and_b32_e32 v97, 0xffff0000, v63
	v_lshlrev_b32_e32 v59, 16, v106
	v_lshlrev_b32_e32 v58, 16, v108
	v_lshlrev_b32_e32 v63, 16, v107
	v_lshlrev_b32_e32 v62, 16, v109
	v_and_b32_e32 v61, 0xffff0000, v107
	v_and_b32_e32 v60, 0xffff0000, v109
	v_pk_fma_f32 v[106:107], v[64:65], v[64:65], v[116:117]
	v_pk_mul_f32 v[108:109], v[56:57], v[56:57]
	v_pk_fma_f32 v[106:107], v[68:69], v[68:69], v[106:107]
	v_pk_fma_f32 v[108:109], v[58:59], v[58:59], v[108:109]
	v_and_b32_e32 v85, 0xffff0000, v76
	v_and_b32_e32 v80, 0xffff0000, v110
	v_and_b32_e32 v84, 0xffff0000, v112
	v_pk_fma_f32 v[134:135], v[70:71], v[70:71], v[106:107]
	v_pk_fma_f32 v[106:107], v[62:63], v[62:63], v[108:109]
	v_lshlrev_b32_e32 v75, 16, v76
	v_lshlrev_b32_e32 v72, 16, v110
	v_lshlrev_b32_e32 v74, 16, v112
	v_pk_fma_f32 v[136:137], v[60:61], v[60:61], v[106:107]
	v_pk_mul_f32 v[106:107], v[80:81], v[80:81]
	v_pk_mul_f32 v[108:109], v[84:85], v[84:85]
	v_lshlrev_b32_e32 v91, 16, v77
	v_lshlrev_b32_e32 v86, 16, v111
	v_lshlrev_b32_e32 v90, 16, v113
	v_pk_fma_f32 v[106:107], v[72:73], v[72:73], v[106:107]
	v_pk_fma_f32 v[108:109], v[74:75], v[74:75], v[108:109]
	v_and_b32_e32 v103, 0xffff0000, v77
	v_and_b32_e32 v96, 0xffff0000, v111
	v_and_b32_e32 v102, 0xffff0000, v113
	v_pk_fma_f32 v[106:107], v[86:87], v[86:87], v[106:107]
	v_pk_fma_f32 v[108:109], v[90:91], v[90:91], v[108:109]
	v_and_b32_e32 v89, 0xffff0000, v104
	v_and_b32_e32 v88, 0xffff0000, v114
	v_pk_fma_f32 v[106:107], v[96:97], v[96:97], v[106:107]
	v_pk_fma_f32 v[108:109], v[102:103], v[102:103], v[108:109]
	v_lshlrev_b32_e32 v77, 16, v104
	v_lshlrev_b32_e32 v76, 16, v114
	v_pk_add_f32 v[106:107], v[106:107], v[108:109]
	v_pk_mul_f32 v[108:109], v[88:89], v[88:89]
	v_lshlrev_b32_e32 v93, 16, v105
	v_lshlrev_b32_e32 v92, 16, v115
	v_pk_fma_f32 v[108:109], v[76:77], v[76:77], v[108:109]
	v_and_b32_e32 v105, 0xffff0000, v105
	v_and_b32_e32 v104, 0xffff0000, v115
	v_pk_fma_f32 v[108:109], v[92:93], v[92:93], v[108:109]
	v_and_b32_e32 v117, 0xffff0000, v120
	v_and_b32_e32 v116, 0xffff0000, v122
	v_pk_fma_f32 v[108:109], v[104:105], v[104:105], v[108:109]
	v_lshlrev_b32_e32 v79, 16, v46
	v_lshlrev_b32_e32 v95, 16, v47
	v_and_b32_e32 v99, 0xffff0000, v47
	v_pk_mul_f32 v[46:47], v[82:83], v[82:83]
	v_lshlrev_b32_e32 v114, 16, v122
	v_lshlrev_b32_e32 v115, 16, v120
	v_pk_add_f32 v[106:107], v[106:107], v[108:109]
	v_pk_mul_f32 v[108:109], v[116:117], v[116:117]
	v_pk_fma_f32 v[46:47], v[78:79], v[78:79], v[46:47]
	v_lshlrev_b32_e32 v118, 16, v123
	v_lshlrev_b32_e32 v119, 16, v121
	v_pk_fma_f32 v[108:109], v[114:115], v[114:115], v[108:109]
	v_pk_fma_f32 v[46:47], v[94:95], v[94:95], v[46:47]
	v_and_b32_e32 v121, 0xffff0000, v121
	v_and_b32_e32 v120, 0xffff0000, v123
	v_pk_fma_f32 v[108:109], v[118:119], v[118:119], v[108:109]
	v_pk_fma_f32 v[46:47], v[98:99], v[98:99], v[46:47]
	v_pk_fma_f32 v[108:109], v[120:121], v[120:121], v[108:109]
	v_lshlrev_b32_e32 v110, 16, v131
	v_pk_add_f32 v[106:107], v[106:107], v[108:109]
	v_mov_b32_e32 v108, v136
	v_mov_b32_e32 v109, v46
	v_pk_add_f32 v[122:123], v[106:107], v[108:109]
	v_and_b32_e32 v109, 0xffff0000, v132
	v_and_b32_e32 v108, 0xffff0000, v130
	v_lshlrev_b32_e32 v107, 16, v132
	v_lshlrev_b32_e32 v106, 16, v130
	v_and_b32_e32 v112, 0xffff0000, v131
	v_pk_mul_f32 v[130:131], v[108:109], v[108:109]
	v_lshlrev_b32_e32 v111, 16, v133
	v_pk_fma_f32 v[130:131], v[106:107], v[106:107], v[130:131]
	v_and_b32_e32 v113, 0xffff0000, v133
	v_pk_fma_f32 v[130:131], v[110:111], v[110:111], v[130:131]
	v_mov_b32_e32 v46, v137
	v_pk_fma_f32 v[130:131], v[112:113], v[112:113], v[130:131]
	v_pk_add_f32 v[46:47], v[122:123], v[46:47]
	v_mov_b32_e32 v122, v130
	v_mov_b32_e32 v123, v134
	v_pk_add_f32 v[46:47], v[46:47], v[122:123]
	v_mov_b32_e32 v134, v131
	v_pk_add_f32 v[46:47], v[46:47], v[134:135]
	ds_bpermute_b32 v123, v55, v47
	ds_bpermute_b32 v122, v55, v46
	global_load_dwordx4 v[130:133], v[100:101], off offset:3072 nt
	global_load_dwordx4 v[134:137], v[178:179], off nt
	global_load_dwordx4 v[138:141], v[178:179], off offset:1024 nt
	global_load_dwordx4 v[142:145], v[178:179], off offset:2048 nt
	global_load_dwordx4 v[146:149], v[178:179], off offset:3072 nt
	global_load_dwordx4 v[150:153], v[180:181], off nt
	global_load_dwordx4 v[154:157], v[180:181], off offset:1024 nt
	global_load_dwordx4 v[158:161], v[180:181], off offset:2048 nt
	global_load_dwordx4 v[162:165], v[180:181], off offset:3072 nt
	s_waitcnt lgkmcnt(0)
	v_pk_add_f32 v[46:47], v[46:47], v[122:123]
	ds_bpermute_b32 v123, v124, v47
	ds_bpermute_b32 v122, v124, v46
	v_mov_b32_e32 v186, v73
	v_mov_b32_e32 v187, v81
	v_mov_b32_e32 v188, v87
	v_mov_b32_e32 v189, v97
	s_waitcnt lgkmcnt(0)
	v_pk_add_f32 v[46:47], v[46:47], v[122:123]
	ds_bpermute_b32 v123, v125, v47
	ds_bpermute_b32 v122, v125, v46
	v_mov_b32_e32 v73, v80
	v_mov_b32_e32 v87, v96
	s_waitcnt lgkmcnt(0)
	v_pk_add_f32 v[46:47], v[46:47], v[122:123]
	ds_bpermute_b32 v123, v126, v47
	ds_bpermute_b32 v122, v126, v46
	s_waitcnt lgkmcnt(0)
	v_pk_add_f32 v[44:45], v[46:47], v[122:123]
	ds_bpermute_b32 v47, v127, v45
	ds_bpermute_b32 v46, v127, v44
	v_add_co_u32_e32 v122, vcc, s3, v180
	s_waitcnt lgkmcnt(0)
	v_pk_add_f32 v[44:45], v[44:45], v[46:47]
	ds_bpermute_b32 v47, v128, v45
	ds_bpermute_b32 v46, v128, v44
	v_addc_co_u32_e32 v123, vcc, 0, v181, vcc
	s_waitcnt lgkmcnt(0)
	v_pk_add_f32 v[44:45], v[44:45], v[46:47]
	s_nop 0
	v_pk_fma_f32 v[182:183], v[44:45], s[2:3], v[54:55] op_sel_hi:[1,0,0]
	s_nop 0
	v_mul_f32_e32 v44, 0x4b800000, v183
	v_cmp_gt_f32_e32 vcc, s5, v183
	s_nop 1
	v_cndmask_b32_e32 v44, v183, v44, vcc
	v_rsq_f32_e32 v49, v44
	global_load_dwordx4 v[166:169], v[122:123], off nt
	global_load_dwordx4 v[170:173], v[122:123], off offset:1024 nt
	global_load_dwordx4 v[174:177], v[122:123], off offset:2048 nt
	global_load_dwordx4 v[44:47], v[122:123], off offset:3072 nt
	v_mul_f32_e32 v129, 0x45800000, v49
	v_cndmask_b32_e32 v184, v49, v129, vcc
	v_pk_mul_f32 v[186:187], v[186:187], v[184:185] op_sel_hi:[1,0]
	v_pk_mul_f32 v[188:189], v[188:189], v[184:185] op_sel_hi:[1,0]
	v_pk_fma_f32 v[40:41], v[0:1], v[186:187], v[40:41]
	v_pk_fma_f32 v[42:43], v[2:3], v[188:189], v[42:43]
	global_store_dwordx4 v[100:101], v[40:43], off nt
	v_cmp_gt_f32_e32 vcc, s5, v182
	s_nop 0
	v_mov_b32_e32 v40, v75
	v_mov_b32_e32 v41, v85
	v_mov_b32_e32 v42, v91
	v_mov_b32_e32 v43, v103
	v_pk_mul_f32 v[40:41], v[40:41], v[184:185] op_sel_hi:[1,0]
	v_pk_mul_f32 v[42:43], v[42:43], v[184:185] op_sel_hi:[1,0]
	v_pk_fma_f32 v[36:37], v[4:5], v[40:41], v[36:37]
	v_pk_fma_f32 v[38:39], v[6:7], v[42:43], v[38:39]
	global_store_dwordx4 v[100:101], v[36:39], off offset:1024 nt
	v_mov_b32_e32 v75, v84
	v_mov_b32_e32 v91, v102
	v_mov_b32_e32 v36, v77
	v_mov_b32_e32 v37, v89
	v_mov_b32_e32 v38, v93
	v_mov_b32_e32 v39, v105
	v_pk_mul_f32 v[36:37], v[36:37], v[184:185] op_sel_hi:[1,0]
	v_pk_mul_f32 v[38:39], v[38:39], v[184:185] op_sel_hi:[1,0]
	v_pk_fma_f32 v[32:33], v[8:9], v[36:37], v[32:33]
	v_pk_fma_f32 v[34:35], v[10:11], v[38:39], v[34:35]
	global_store_dwordx4 v[100:101], v[32:35], off offset:2048 nt
	v_mul_f32_e32 v36, 0x4b800000, v182
	v_cndmask_b32_e32 v36, v182, v36, vcc
	v_mov_b32_e32 v32, v115
	v_mov_b32_e32 v33, v117
	v_mov_b32_e32 v34, v119
	v_mov_b32_e32 v35, v121
	v_pk_mul_f32 v[32:33], v[32:33], v[184:185] op_sel_hi:[1,0]
	v_pk_mul_f32 v[34:35], v[34:35], v[184:185] op_sel_hi:[1,0]
	s_waitcnt vmcnt(15)
	v_pk_fma_f32 v[32:33], v[12:13], v[32:33], v[130:131]
	v_pk_fma_f32 v[34:35], v[14:15], v[34:35], v[132:133]
	global_store_dwordx4 v[100:101], v[32:35], off offset:3072 nt
	v_rsq_f32_e32 v36, v36
	v_mov_b32_e32 v77, v88
	v_mov_b32_e32 v32, v78
	v_mov_b32_e32 v33, v82
	v_mov_b32_e32 v34, v94
	v_mov_b32_e32 v35, v98
	v_pk_mul_f32 v[32:33], v[32:33], v[184:185] op_sel_hi:[1,0]
	v_pk_mul_f32 v[34:35], v[34:35], v[184:185] op_sel_hi:[1,0]
	s_waitcnt vmcnt(15)
	v_pk_fma_f32 v[32:33], v[16:17], v[32:33], v[134:135]
	v_pk_fma_f32 v[34:35], v[18:19], v[34:35], v[136:137]
	v_mov_b32_e32 v82, v79
	v_mov_b32_e32 v98, v95
	global_store_dwordx4 v[178:179], v[32:35], off nt
	v_mov_b32_e32 v93, v104
	v_mov_b32_e32 v115, v116
	v_pk_mul_f32 v[32:33], v[82:83], v[184:185] op_sel_hi:[1,0]
	v_pk_mul_f32 v[34:35], v[98:99], v[184:185] op_sel_hi:[1,0]
	s_waitcnt vmcnt(15)
	v_pk_fma_f32 v[32:33], v[20:21], v[32:33], v[138:139]
	v_pk_fma_f32 v[34:35], v[22:23], v[34:35], v[140:141]
	global_store_dwordx4 v[178:179], v[32:35], off offset:1024 nt
	v_mov_b32_e32 v119, v120
	s_nop 0
	v_mov_b32_e32 v32, v64
	v_mov_b32_e32 v33, v66
	v_mov_b32_e32 v34, v68
	v_mov_b32_e32 v35, v70
	v_pk_mul_f32 v[32:33], v[32:33], v[184:185] op_sel_hi:[1,0]
	v_pk_mul_f32 v[34:35], v[34:35], v[184:185] op_sel_hi:[1,0]
	s_waitcnt vmcnt(15)
	v_pk_fma_f32 v[32:33], v[24:25], v[32:33], v[142:143]
	v_pk_fma_f32 v[34:35], v[26:27], v[34:35], v[144:145]
	v_mov_b32_e32 v66, v65
	v_mov_b32_e32 v70, v69
	global_store_dwordx4 v[178:179], v[32:35], off offset:2048 nt
	s_nop 1
	v_pk_mul_f32 v[32:33], v[66:67], v[184:185] op_sel_hi:[1,0]
	v_pk_mul_f32 v[34:35], v[70:71], v[184:185] op_sel_hi:[1,0]
	s_waitcnt vmcnt(15)
	v_pk_fma_f32 v[32:33], v[28:29], v[32:33], v[146:147]
	v_pk_fma_f32 v[34:35], v[30:31], v[34:35], v[148:149]
	global_store_dwordx4 v[178:179], v[32:35], off offset:3072 nt
	s_nop 1
	v_mul_f32_e32 v32, 0x45800000, v36
	v_cndmask_b32_e32 v36, v36, v32, vcc
	v_pk_mul_f32 v[32:33], v[72:73], v[36:37] op_sel_hi:[1,0]
	v_pk_mul_f32 v[34:35], v[86:87], v[36:37] op_sel_hi:[1,0]
	s_waitcnt vmcnt(15)
	v_pk_fma_f32 v[32:33], v[0:1], v[32:33], v[150:151]
	v_pk_fma_f32 v[34:35], v[2:3], v[34:35], v[152:153]
	global_store_dwordx4 v[180:181], v[32:35], off nt
	v_cmp_lt_i32_e32 vcc, s6, v48
	s_or_b64 s[0:1], vcc, s[0:1]
	v_pk_mul_f32 v[32:33], v[74:75], v[36:37] op_sel_hi:[1,0]
	v_pk_mul_f32 v[34:35], v[90:91], v[36:37] op_sel_hi:[1,0]
	s_waitcnt vmcnt(15)
	v_pk_fma_f32 v[32:33], v[4:5], v[32:33], v[154:155]
	v_pk_fma_f32 v[34:35], v[6:7], v[34:35], v[156:157]
	global_store_dwordx4 v[180:181], v[32:35], off offset:1024 nt
	s_nop 1
	v_pk_mul_f32 v[32:33], v[76:77], v[36:37] op_sel_hi:[1,0]
	v_pk_mul_f32 v[34:35], v[92:93], v[36:37] op_sel_hi:[1,0]
	s_waitcnt vmcnt(15)
	v_pk_fma_f32 v[32:33], v[8:9], v[32:33], v[158:159]
	v_pk_fma_f32 v[34:35], v[10:11], v[34:35], v[160:161]
	global_store_dwordx4 v[180:181], v[32:35], off offset:2048 nt
	s_nop 1
	v_pk_mul_f32 v[32:33], v[114:115], v[36:37] op_sel_hi:[1,0]
	v_pk_mul_f32 v[34:35], v[118:119], v[36:37] op_sel_hi:[1,0]
	s_waitcnt vmcnt(15)
	v_pk_fma_f32 v[32:33], v[12:13], v[32:33], v[162:163]
	v_pk_fma_f32 v[34:35], v[14:15], v[34:35], v[164:165]
	global_store_dwordx4 v[180:181], v[32:35], off offset:3072 nt
	s_nop 1
	v_mov_b32_e32 v32, v58
	v_mov_b32_e32 v33, v56
	v_mov_b32_e32 v34, v62
	v_mov_b32_e32 v35, v60
	v_pk_mul_f32 v[32:33], v[32:33], v[36:37] op_sel_hi:[1,0]
	v_pk_mul_f32 v[34:35], v[34:35], v[36:37] op_sel_hi:[1,0]
	s_waitcnt vmcnt(15)
	v_pk_fma_f32 v[32:33], v[16:17], v[32:33], v[166:167]
	v_pk_fma_f32 v[34:35], v[18:19], v[34:35], v[168:169]
	v_mov_b32_e32 v56, v59
	v_mov_b32_e32 v60, v63
	global_store_dwordx4 v[122:123], v[32:35], off nt
	s_nop 1
	v_pk_mul_f32 v[32:33], v[56:57], v[36:37] op_sel_hi:[1,0]
	v_pk_mul_f32 v[34:35], v[60:61], v[36:37] op_sel_hi:[1,0]
	s_waitcnt vmcnt(15)
	v_pk_fma_f32 v[32:33], v[20:21], v[32:33], v[170:171]
	v_pk_fma_f32 v[34:35], v[22:23], v[34:35], v[172:173]
	global_store_dwordx4 v[122:123], v[32:35], off offset:1024 nt
	s_nop 1
	v_mov_b32_e32 v32, v106
	v_mov_b32_e32 v33, v108
	v_mov_b32_e32 v34, v110
	v_mov_b32_e32 v35, v112
	v_pk_mul_f32 v[32:33], v[32:33], v[36:37] op_sel_hi:[1,0]
	v_pk_mul_f32 v[34:35], v[34:35], v[36:37] op_sel_hi:[1,0]
	s_waitcnt vmcnt(15)
	v_pk_fma_f32 v[32:33], v[24:25], v[32:33], v[174:175]
	v_pk_fma_f32 v[34:35], v[26:27], v[34:35], v[176:177]
	v_mov_b32_e32 v108, v107
	v_mov_b32_e32 v112, v111
	global_store_dwordx4 v[122:123], v[32:35], off offset:2048 nt
	s_nop 1
	v_pk_mul_f32 v[32:33], v[108:109], v[36:37] op_sel_hi:[1,0]
	v_pk_mul_f32 v[34:35], v[112:113], v[36:37] op_sel_hi:[1,0]
	s_waitcnt vmcnt(15)
	v_pk_fma_f32 v[32:33], v[28:29], v[32:33], v[44:45]
	v_pk_fma_f32 v[34:35], v[30:31], v[34:35], v[46:47]
	global_store_dwordx4 v[122:123], v[32:35], off offset:3072 nt
	s_andn2_b64 exec, exec, s[0:1]
	s_cbranch_execnz .LBB0_1491
